# hand-written out-projection residual epilogues (batched loads), attention epilogue gate loads hoisted, LN loop rewritten with prefetch, counted lgkmcnt in GEMM
# speedup vs baseline: 1.0442x; 1.0442x over previous
; #define LDSR(dst, addr, off) asm volatile("ds_read_b128 %0, %1 offset:%2" : "=&v"(dst) : "v"(addr), "n"(off))
; #define LDSR(dst, addr, off) asm volatile("ds_read_b128 %0, %1 offset:%2" : "=&v"(dst) : "v"(addr), "n"(off))
; template <class AP, class BP, class Epi>
; DI void mfma_gemm_big_tile(const AP& aptr, const BP& bptr, int m0, int n0, int K, const Epi& epi, bf16* lds) {
;     ...
;   for (int ks = 0; ks < nk; ++ks) {
;     if (ks + 2 < nk) BG_ISSUE(nxt, ks + 2);
;     const unsigned sa = lbase + (unsigned)(cur * BG_STAGE * 2) + a_off, sb = lbase + (unsigned)(cur * BG_STAGE * 2) + b_off;
;     bf16x8 af[8], bfr[4];
;     LDSR(bfr[0], sb, 0); LDSR(bfr[1], sb, 1024); LDSR(bfr[2], sb, 2048); LDSR(bfr[3], sb, 3072);
;     LDSR(af[0], sa, 0); LDSR(af[1], sa, 1024); LDSR(af[2], sa, 2048); LDSR(af[3], sa, 3072);
;     LDSR(af[4], sa, 4096); LDSR(af[5], sa, 5120); LDSR(af[6], sa, 6144); LDSR(af[7], sa, 7168);
;     asm volatile("s_waitcnt lgkmcnt(0)" : "+v"(af[0]), "+v"(af[1]), "+v"(af[2]), "+v"(af[3]), "+v"(af[4]), "+v"(af[5]), "+v"(af[6]), "+v"(af[7]),
;                  "+v"(bfr[0]), "+v"(bfr[1]), "+v"(bfr[2]), "+v"(bfr[3]) : : "memory");
; #pragma unroll
;     for (int i = 0; i < 8; ++i)
; #pragma unroll
;       for (int j = 0; j < 4; ++j) acc[i][j] = __builtin_amdgcn_mfma_f32_16x16x32_bf16(bfr[j], af[i], acc[i][j], 0, 0, 0);
;     if (ks + 2 < nk) asm volatile("s_waitcnt vmcnt(6)\n\ts_barrier" ::: "memory");
;     else asm volatile("s_waitcnt vmcnt(0)\n\ts_barrier" ::: "memory");
;     cur = (cur == 2) ? 0 : cur + 1; nxt = (nxt == 2) ? 0 : nxt + 1;
;   }
.LBB0_239:
	s_mul_i32 s6, s18, 0x6000
	v_add_u32_e32 v145, s6, v143
	v_add_u32_e32 v159, s6, v144
	ds_read_b128 v[146:149], v159 offset:0
	ds_read_b128 v[150:153], v159 offset:0x400
	ds_read_b128 v[154:157], v159 offset:0x800
	ds_read_b128 v[162:165], v159 offset:0xc00
	ds_read_b128 v[166:169], v145 offset:0
	ds_read_b128 v[182:185], v145 offset:0x400
	ds_read_b128 v[192:195], v145 offset:0x800
	ds_read_b128 v[196:199], v145 offset:0xc00
	ds_read_b128 v[200:203], v145 offset:0x1000
	ds_read_b128 v[204:207], v145 offset:0x1400
	ds_read_b128 v[208:211], v145 offset:0x1800
	ds_read_b128 v[212:215], v145 offset:0x1c00
	s_mov_b64 s[6:7], -1
	s_waitcnt lgkmcnt(7)
	s_and_b64 vcc, exec, s[4:5]
	v_mfma_f32_16x16x32_bf16 v[126:129], v[146:149], v[166:169], v[126:129]
	v_mfma_f32_16x16x32_bf16 v[122:125], v[150:153], v[166:169], v[122:125]
	v_mfma_f32_16x16x32_bf16 v[118:121], v[154:157], v[166:169], v[118:121]
	v_mfma_f32_16x16x32_bf16 v[114:117], v[162:165], v[166:169], v[114:117]
	s_waitcnt lgkmcnt(6)
	v_mfma_f32_16x16x32_bf16 v[110:113], v[146:149], v[182:185], v[110:113]
	v_mfma_f32_16x16x32_bf16 v[106:109], v[150:153], v[182:185], v[106:109]
	v_mfma_f32_16x16x32_bf16 v[102:105], v[154:157], v[182:185], v[102:105]
	v_mfma_f32_16x16x32_bf16 v[98:101], v[162:165], v[182:185], v[98:101]
	s_waitcnt lgkmcnt(5)
	v_mfma_f32_16x16x32_bf16 v[94:97], v[146:149], v[192:195], v[94:97]
	v_mfma_f32_16x16x32_bf16 v[90:93], v[150:153], v[192:195], v[90:93]
	v_mfma_f32_16x16x32_bf16 v[86:89], v[154:157], v[192:195], v[86:89]
	v_mfma_f32_16x16x32_bf16 v[82:85], v[162:165], v[192:195], v[82:85]
	s_waitcnt lgkmcnt(4)
	v_mfma_f32_16x16x32_bf16 v[78:81], v[146:149], v[196:199], v[78:81]
	v_mfma_f32_16x16x32_bf16 v[74:77], v[150:153], v[196:199], v[74:77]
	v_mfma_f32_16x16x32_bf16 v[70:73], v[154:157], v[196:199], v[70:73]
	v_mfma_f32_16x16x32_bf16 v[66:69], v[162:165], v[196:199], v[66:69]
	s_waitcnt lgkmcnt(3)
	v_mfma_f32_16x16x32_bf16 v[62:65], v[146:149], v[200:203], v[62:65]
	v_mfma_f32_16x16x32_bf16 v[58:61], v[150:153], v[200:203], v[58:61]
	v_mfma_f32_16x16x32_bf16 v[54:57], v[154:157], v[200:203], v[54:57]
	v_mfma_f32_16x16x32_bf16 v[50:53], v[162:165], v[200:203], v[50:53]
	s_waitcnt lgkmcnt(2)
	v_mfma_f32_16x16x32_bf16 v[46:49], v[146:149], v[204:207], v[46:49]
	v_mfma_f32_16x16x32_bf16 v[42:45], v[150:153], v[204:207], v[42:45]
	v_mfma_f32_16x16x32_bf16 v[38:41], v[154:157], v[204:207], v[38:41]
	v_mfma_f32_16x16x32_bf16 v[34:37], v[162:165], v[204:207], v[34:37]
	s_waitcnt lgkmcnt(1)
	v_mfma_f32_16x16x32_bf16 v[30:33], v[146:149], v[208:211], v[30:33]
	v_mfma_f32_16x16x32_bf16 v[26:29], v[150:153], v[208:211], v[26:29]
	v_mfma_f32_16x16x32_bf16 v[22:25], v[154:157], v[208:211], v[22:25]
	v_mfma_f32_16x16x32_bf16 v[18:21], v[162:165], v[208:211], v[18:21]
	s_waitcnt lgkmcnt(0)
	v_mfma_f32_16x16x32_bf16 v[14:17], v[146:149], v[212:215], v[14:17]
	v_mfma_f32_16x16x32_bf16 v[10:13], v[150:153], v[212:215], v[10:13]
	v_mfma_f32_16x16x32_bf16 v[6:9], v[154:157], v[212:215], v[6:9]
	v_mfma_f32_16x16x32_bf16 v[2:5], v[162:165], v[212:215], v[2:5]
	s_cbranch_vccz .LBB0_241
	s_waitcnt vmcnt(0)
	s_barrier
	s_mov_b64 s[6:7], 0

; #define LDSR(dst, addr, off) asm volatile("ds_read_b128 %0, %1 offset:%2" : "=&v"(dst) : "v"(addr), "n"(off))
; #define LDSR(dst, addr, off) asm volatile("ds_read_b128 %0, %1 offset:%2" : "=&v"(dst) : "v"(addr), "n"(off))
; template <class AP, class BP, class Epi>
; DI void mfma_gemm_big_tile(const AP& aptr, const BP& bptr, int m0, int n0, int K, const Epi& epi, bf16* lds) {
;     ...
;   for (int ks = 0; ks < nk; ++ks) {
;     if (ks + 2 < nk) BG_ISSUE(nxt, ks + 2);
;     const unsigned sa = lbase + (unsigned)(cur * BG_STAGE * 2) + a_off, sb = lbase + (unsigned)(cur * BG_STAGE * 2) + b_off;
;     bf16x8 af[8], bfr[4];
;     LDSR(bfr[0], sb, 0); LDSR(bfr[1], sb, 1024); LDSR(bfr[2], sb, 2048); LDSR(bfr[3], sb, 3072);
;     LDSR(af[0], sa, 0); LDSR(af[1], sa, 1024); LDSR(af[2], sa, 2048); LDSR(af[3], sa, 3072);
;     LDSR(af[4], sa, 4096); LDSR(af[5], sa, 5120); LDSR(af[6], sa, 6144); LDSR(af[7], sa, 7168);
;     asm volatile("s_waitcnt lgkmcnt(0)" : "+v"(af[0]), "+v"(af[1]), "+v"(af[2]), "+v"(af[3]), "+v"(af[4]), "+v"(af[5]), "+v"(af[6]), "+v"(af[7]),
;                  "+v"(bfr[0]), "+v"(bfr[1]), "+v"(bfr[2]), "+v"(bfr[3]) : : "memory");
; #pragma unroll
;     for (int i = 0; i < 8; ++i)
; #pragma unroll
;       for (int j = 0; j < 4; ++j) acc[i][j] = __builtin_amdgcn_mfma_f32_16x16x32_bf16(bfr[j], af[i], acc[i][j], 0, 0, 0);
;     if (ks + 2 < nk) asm volatile("s_waitcnt vmcnt(6)\n\ts_barrier" ::: "memory");
;     else asm volatile("s_waitcnt vmcnt(0)\n\ts_barrier" ::: "memory");
;     cur = (cur == 2) ? 0 : cur + 1; nxt = (nxt == 2) ? 0 : nxt + 1;
;   }
.LBB0_252:
	s_mul_i32 s6, s19, 0x6000
	v_add_u32_e32 v145, s6, v143
	v_add_u32_e32 v159, s6, v144
	ds_read_b128 v[146:149], v159 offset:0
	ds_read_b128 v[150:153], v159 offset:0x400
	ds_read_b128 v[154:157], v159 offset:0x800
	ds_read_b128 v[162:165], v159 offset:0xc00
	ds_read_b128 v[166:169], v145 offset:0
	ds_read_b128 v[182:185], v145 offset:0x400
	ds_read_b128 v[192:195], v145 offset:0x800
	ds_read_b128 v[196:199], v145 offset:0xc00
	ds_read_b128 v[200:203], v145 offset:0x1000
	ds_read_b128 v[204:207], v145 offset:0x1400
	ds_read_b128 v[208:211], v145 offset:0x1800
	ds_read_b128 v[212:215], v145 offset:0x1c00
	s_mov_b64 s[6:7], -1
	s_waitcnt lgkmcnt(7)
	s_and_b64 vcc, exec, s[4:5]
	v_mfma_f32_16x16x32_bf16 v[126:129], v[146:149], v[166:169], v[126:129]
	v_mfma_f32_16x16x32_bf16 v[122:125], v[150:153], v[166:169], v[122:125]
	v_mfma_f32_16x16x32_bf16 v[118:121], v[154:157], v[166:169], v[118:121]
	v_mfma_f32_16x16x32_bf16 v[114:117], v[162:165], v[166:169], v[114:117]
	s_waitcnt lgkmcnt(6)
	v_mfma_f32_16x16x32_bf16 v[110:113], v[146:149], v[182:185], v[110:113]
	v_mfma_f32_16x16x32_bf16 v[106:109], v[150:153], v[182:185], v[106:109]
	v_mfma_f32_16x16x32_bf16 v[102:105], v[154:157], v[182:185], v[102:105]
	v_mfma_f32_16x16x32_bf16 v[98:101], v[162:165], v[182:185], v[98:101]
	s_waitcnt lgkmcnt(5)
	v_mfma_f32_16x16x32_bf16 v[94:97], v[146:149], v[192:195], v[94:97]
	v_mfma_f32_16x16x32_bf16 v[90:93], v[150:153], v[192:195], v[90:93]
	v_mfma_f32_16x16x32_bf16 v[86:89], v[154:157], v[192:195], v[86:89]
	v_mfma_f32_16x16x32_bf16 v[82:85], v[162:165], v[192:195], v[82:85]
	s_waitcnt lgkmcnt(4)
	v_mfma_f32_16x16x32_bf16 v[78:81], v[146:149], v[196:199], v[78:81]
	v_mfma_f32_16x16x32_bf16 v[74:77], v[150:153], v[196:199], v[74:77]
	v_mfma_f32_16x16x32_bf16 v[70:73], v[154:157], v[196:199], v[70:73]
	v_mfma_f32_16x16x32_bf16 v[66:69], v[162:165], v[196:199], v[66:69]
	s_waitcnt lgkmcnt(3)
	v_mfma_f32_16x16x32_bf16 v[62:65], v[146:149], v[200:203], v[62:65]
	v_mfma_f32_16x16x32_bf16 v[58:61], v[150:153], v[200:203], v[58:61]
	v_mfma_f32_16x16x32_bf16 v[54:57], v[154:157], v[200:203], v[54:57]
	v_mfma_f32_16x16x32_bf16 v[50:53], v[162:165], v[200:203], v[50:53]
	s_waitcnt lgkmcnt(2)
	v_mfma_f32_16x16x32_bf16 v[46:49], v[146:149], v[204:207], v[46:49]
	v_mfma_f32_16x16x32_bf16 v[42:45], v[150:153], v[204:207], v[42:45]
	v_mfma_f32_16x16x32_bf16 v[38:41], v[154:157], v[204:207], v[38:41]
	v_mfma_f32_16x16x32_bf16 v[34:37], v[162:165], v[204:207], v[34:37]
	s_waitcnt lgkmcnt(1)
	v_mfma_f32_16x16x32_bf16 v[30:33], v[146:149], v[208:211], v[30:33]
	v_mfma_f32_16x16x32_bf16 v[26:29], v[150:153], v[208:211], v[26:29]
	v_mfma_f32_16x16x32_bf16 v[22:25], v[154:157], v[208:211], v[22:25]
	v_mfma_f32_16x16x32_bf16 v[18:21], v[162:165], v[208:211], v[18:21]
	s_waitcnt lgkmcnt(0)
	v_mfma_f32_16x16x32_bf16 v[14:17], v[146:149], v[212:215], v[14:17]
	v_mfma_f32_16x16x32_bf16 v[10:13], v[150:153], v[212:215], v[10:13]
	v_mfma_f32_16x16x32_bf16 v[6:9], v[154:157], v[212:215], v[6:9]
	v_mfma_f32_16x16x32_bf16 v[2:5], v[162:165], v[212:215], v[2:5]
	s_cbranch_vccz .LBB0_254
	s_waitcnt vmcnt(0)
	s_barrier
	s_mov_b64 s[6:7], 0

; #define LDSR(dst, addr, off) asm volatile("ds_read_b128 %0, %1 offset:%2" : "=&v"(dst) : "v"(addr), "n"(off))
; #define LDSR(dst, addr, off) asm volatile("ds_read_b128 %0, %1 offset:%2" : "=&v"(dst) : "v"(addr), "n"(off))
; template <class AP, class BP, class Epi>
; DI void mfma_gemm_big_tile(const AP& aptr, const BP& bptr, int m0, int n0, int K, const Epi& epi, bf16* lds) {
;     ...
;   for (int ks = 0; ks < nk; ++ks) {
;     if (ks + 2 < nk) BG_ISSUE(nxt, ks + 2);
;     const unsigned sa = lbase + (unsigned)(cur * BG_STAGE * 2) + a_off, sb = lbase + (unsigned)(cur * BG_STAGE * 2) + b_off;
;     bf16x8 af[8], bfr[4];
;     LDSR(bfr[0], sb, 0); LDSR(bfr[1], sb, 1024); LDSR(bfr[2], sb, 2048); LDSR(bfr[3], sb, 3072);
;     LDSR(af[0], sa, 0); LDSR(af[1], sa, 1024); LDSR(af[2], sa, 2048); LDSR(af[3], sa, 3072);
;     LDSR(af[4], sa, 4096); LDSR(af[5], sa, 5120); LDSR(af[6], sa, 6144); LDSR(af[7], sa, 7168);
;     asm volatile("s_waitcnt lgkmcnt(0)" : "+v"(af[0]), "+v"(af[1]), "+v"(af[2]), "+v"(af[3]), "+v"(af[4]), "+v"(af[5]), "+v"(af[6]), "+v"(af[7]),
;                  "+v"(bfr[0]), "+v"(bfr[1]), "+v"(bfr[2]), "+v"(bfr[3]) : : "memory");
; #pragma unroll
;     for (int i = 0; i < 8; ++i)
; #pragma unroll
;       for (int j = 0; j < 4; ++j) acc[i][j] = __builtin_amdgcn_mfma_f32_16x16x32_bf16(bfr[j], af[i], acc[i][j], 0, 0, 0);
;     if (ks + 2 < nk) asm volatile("s_waitcnt vmcnt(6)\n\ts_barrier" ::: "memory");
;     else asm volatile("s_waitcnt vmcnt(0)\n\ts_barrier" ::: "memory");
;     cur = (cur == 2) ? 0 : cur + 1; nxt = (nxt == 2) ? 0 : nxt + 1;
;   }
.LBB0_499:
	s_mul_i32 s6, s18, 0x6000
	v_add_u32_e32 v145, s6, v143
	v_add_u32_e32 v159, s6, v144
	ds_read_b128 v[146:149], v159 offset:0
	ds_read_b128 v[150:153], v159 offset:0x400
	ds_read_b128 v[154:157], v159 offset:0x800
	ds_read_b128 v[162:165], v159 offset:0xc00
	ds_read_b128 v[166:169], v145 offset:0
	ds_read_b128 v[192:195], v145 offset:0x400
	ds_read_b128 v[196:199], v145 offset:0x800
	ds_read_b128 v[200:203], v145 offset:0xc00
	ds_read_b128 v[204:207], v145 offset:0x1000
	ds_read_b128 v[208:211], v145 offset:0x1400
	ds_read_b128 v[212:215], v145 offset:0x1800
	ds_read_b128 v[216:219], v145 offset:0x1c00
	s_mov_b64 s[6:7], -1
	s_waitcnt lgkmcnt(7)
	s_and_b64 vcc, exec, s[4:5]
	v_mfma_f32_16x16x32_bf16 v[126:129], v[146:149], v[166:169], v[126:129]
	v_mfma_f32_16x16x32_bf16 v[122:125], v[150:153], v[166:169], v[122:125]
	v_mfma_f32_16x16x32_bf16 v[118:121], v[154:157], v[166:169], v[118:121]
	v_mfma_f32_16x16x32_bf16 v[114:117], v[162:165], v[166:169], v[114:117]
	s_waitcnt lgkmcnt(6)
	v_mfma_f32_16x16x32_bf16 v[110:113], v[146:149], v[192:195], v[110:113]
	v_mfma_f32_16x16x32_bf16 v[106:109], v[150:153], v[192:195], v[106:109]
	v_mfma_f32_16x16x32_bf16 v[102:105], v[154:157], v[192:195], v[102:105]
	v_mfma_f32_16x16x32_bf16 v[98:101], v[162:165], v[192:195], v[98:101]
	s_waitcnt lgkmcnt(5)
	v_mfma_f32_16x16x32_bf16 v[94:97], v[146:149], v[196:199], v[94:97]
	v_mfma_f32_16x16x32_bf16 v[90:93], v[150:153], v[196:199], v[90:93]
	v_mfma_f32_16x16x32_bf16 v[86:89], v[154:157], v[196:199], v[86:89]
	v_mfma_f32_16x16x32_bf16 v[82:85], v[162:165], v[196:199], v[82:85]
	s_waitcnt lgkmcnt(4)
	v_mfma_f32_16x16x32_bf16 v[78:81], v[146:149], v[200:203], v[78:81]
	v_mfma_f32_16x16x32_bf16 v[74:77], v[150:153], v[200:203], v[74:77]
	v_mfma_f32_16x16x32_bf16 v[70:73], v[154:157], v[200:203], v[70:73]
	v_mfma_f32_16x16x32_bf16 v[66:69], v[162:165], v[200:203], v[66:69]
	s_waitcnt lgkmcnt(3)
	v_mfma_f32_16x16x32_bf16 v[62:65], v[146:149], v[204:207], v[62:65]
	v_mfma_f32_16x16x32_bf16 v[58:61], v[150:153], v[204:207], v[58:61]
	v_mfma_f32_16x16x32_bf16 v[54:57], v[154:157], v[204:207], v[54:57]
	v_mfma_f32_16x16x32_bf16 v[50:53], v[162:165], v[204:207], v[50:53]
	s_waitcnt lgkmcnt(2)
	v_mfma_f32_16x16x32_bf16 v[46:49], v[146:149], v[208:211], v[46:49]
	v_mfma_f32_16x16x32_bf16 v[42:45], v[150:153], v[208:211], v[42:45]
	v_mfma_f32_16x16x32_bf16 v[38:41], v[154:157], v[208:211], v[38:41]
	v_mfma_f32_16x16x32_bf16 v[34:37], v[162:165], v[208:211], v[34:37]
	s_waitcnt lgkmcnt(1)
	v_mfma_f32_16x16x32_bf16 v[30:33], v[146:149], v[212:215], v[30:33]
	v_mfma_f32_16x16x32_bf16 v[26:29], v[150:153], v[212:215], v[26:29]
	v_mfma_f32_16x16x32_bf16 v[22:25], v[154:157], v[212:215], v[22:25]
	v_mfma_f32_16x16x32_bf16 v[18:21], v[162:165], v[212:215], v[18:21]
	s_waitcnt lgkmcnt(0)
	v_mfma_f32_16x16x32_bf16 v[14:17], v[146:149], v[216:219], v[14:17]
	v_mfma_f32_16x16x32_bf16 v[10:13], v[150:153], v[216:219], v[10:13]
	v_mfma_f32_16x16x32_bf16 v[6:9], v[154:157], v[216:219], v[6:9]
	v_mfma_f32_16x16x32_bf16 v[2:5], v[162:165], v[216:219], v[2:5]
	s_cbranch_vccz .LBB0_501
	s_waitcnt vmcnt(0)
	s_barrier
	s_mov_b64 s[6:7], 0

; DI float silu(float x) { return x * __builtin_amdgcn_rcpf(1.f + __expf(-x)); }
;   DI bf16* HY() const { return (bf16*)(p.ws + WS_HY); }
;   DI bf16* P() const { return (bf16*)(p.ws + WS_P); }
; DI u32x2 pk4(f32x4 v) { return u32x2{pk2(v[0], v[1]), pk2(v[2], v[3])}; }
; DI f32x4 unpk4(u32x2 u) { return f32x4{__uint_as_float(u[0] << 16), __uint_as_float(u[0] & 0xffff0000u), __uint_as_float(u[1] << 16), __uint_as_float(u[1] & 0xffff0000u)}; }
; DI void attn_item(const Ctx& c, int item, bf16* lds) {
;     ...
;   __syncthreads();
; #pragma unroll
;   for (int qs = 0; qs < 2; ++qs) {
;     const float inv = 1.f / xhalf_sum(lsum[qs]);
;     const int row = rowbase + wave * 64 + qs * 32 + r;
;     const bf16* mg = c.P() + (size_t)row * LDP + C_MG + h * 64;
;     bf16* dst = c.HY() + (size_t)row * D + 512 + h * 64;
; #pragma unroll
;     for (int vt = 0; vt < 2; ++vt)
; #pragma unroll
;       for (int g = 0; g < 4; ++g) {
;         const int vd = 32 * vt + 8 * g + 4 * hh;
;         const f32x4 g4 = unpk4(*(const u32x2*)(mg + vd));
;         f32x4 o = {ot[qs][vt][4 * g] * inv * silu(g4[0]), ot[qs][vt][4 * g + 1] * inv * silu(g4[1]), ot[qs][vt][4 * g + 2] * inv * silu(g4[2]), ot[qs][vt][4 * g + 3] * inv * silu(g4[3])};
;         *(u32x2*)(dst + vd) = pk4(o);
;       }
;   }
.LBB0_820:
	v_mov_b32_e32 v2, v0
	s_nop 1
	v_permlane32_swap_b32_e32 v0, v2
	v_add_f32_e32 v0, v0, v2
	v_div_scale_f32 v2, s[4:5], v0, v0, 1.0
	v_rcp_f32_e32 v3, v2
	s_lshl_b32 s1, s7, 5
	s_and_b32 s1, s1, 0xffffe000
	s_or_b32 s1, s1, s8
	v_fma_f32 v4, -v2, v3, 1.0
	v_fmac_f32_e32 v3, v4, v3
	v_div_scale_f32 v4, vcc, 1.0, v0, 1.0
	v_mul_f32_e32 v5, v4, v3
	v_fma_f32 v6, -v2, v5, v4
	v_fmac_f32_e32 v5, v6, v3
	v_fma_f32 v2, -v2, v5, v4
	v_div_fmas_f32 v2, v2, v3, v5
	v_add_u32_e32 v9, s1, v157
	v_div_fixup_f32 v0, v2, v0, 1.0
	v_mov_b64_e32 v[2:3], s[88:89]
	v_mad_i64_i32 v[4:5], s[4:5], v9, s78, v[2:3]
	s_lshl_b32 s0, s0, 7
	s_mov_b32 s5, s85
	s_and_b32 s4, s0, 0x380
	v_lshl_add_u64 v[6:7], v[4:5], 0, s[4:5]
	s_movk_i32 s2, 0xf400
	v_mov_b32_e32 v157, v1
	v_mad_i64_i32 v[4:5], s[0:1], v9, s2, v[4:5]
	v_lshl_add_u64 v[6:7], v[6:7], 0, v[156:157]
	s_mov_b64 s[8:9], 0x3228f80
	v_lshl_add_u64 v[10:11], v[4:5], 0, s[4:5]
	v_lshl_add_u64 v[4:5], v[6:7], 0, s[8:9]
	v_add_co_u32_e32 v6, vcc, s81, v6
	s_nop 1
	v_addc_co_u32_e32 v7, vcc, 0, v7, vcc
	s_barrier
	s_mov_b64 s[10:11], 0x28000
	v_lshl_add_u64 v[112:113], v[6:7], 0, s[10:11]
	v_lshl_add_u64 v[114:115], v[4:5], 0, s[10:11]
	global_load_dwordx2 v[80:81], v[6:7], off offset:3968
	global_load_dwordx2 v[82:83], v[4:5], off offset:16
	global_load_dwordx2 v[84:85], v[4:5], off offset:32
	global_load_dwordx2 v[86:87], v[4:5], off offset:48
	global_load_dwordx2 v[88:89], v[4:5], off offset:64
	global_load_dwordx2 v[90:91], v[4:5], off offset:80
	global_load_dwordx2 v[92:93], v[4:5], off offset:96
	global_load_dwordx2 v[94:95], v[4:5], off offset:112
	global_load_dwordx2 v[96:97], v[112:113], off offset:3968
	global_load_dwordx2 v[98:99], v[114:115], off offset:16
	global_load_dwordx2 v[100:101], v[114:115], off offset:32
	global_load_dwordx2 v[102:103], v[114:115], off offset:48
	global_load_dwordx2 v[104:105], v[114:115], off offset:64
	global_load_dwordx2 v[106:107], v[114:115], off offset:80
	global_load_dwordx2 v[108:109], v[114:115], off offset:96
	global_load_dwordx2 v[110:111], v[114:115], off offset:112
	v_pk_mul_f32 v[64:65], v[64:65], v[0:1] op_sel_hi:[1,0]
	v_lshl_add_u64 v[10:11], v[10:11], 0, v[156:157]
	s_mov_b64 s[10:11], 0x1128400
	s_mov_b32 s3, 0x1128000
	v_pk_mul_f32 v[48:49], v[48:49], v[0:1] op_sel_hi:[1,0]
	s_add_i32 s6, s6, s41
	s_cmp_gt_i32 s6, 63
	s_waitcnt vmcnt(15)
	v_lshlrev_b32_e32 v12, 16, v80
	v_and_b32_e32 v13, 0xffff0000, v80
	v_mul_f32_e32 v6, 0xbfb8aa3b, v12
	v_exp_f32_e32 v6, v6
	s_nop 0
	v_add_f32_e32 v6, 1.0, v6
	v_rcp_f32_e32 v14, v6
	v_mul_f32_e32 v6, 0xbfb8aa3b, v13
	v_exp_f32_e32 v6, v6
	s_nop 0
	v_add_f32_e32 v6, 1.0, v6
	v_rcp_f32_e32 v15, v6
	v_lshlrev_b32_e32 v6, 16, v81
	v_and_b32_e32 v7, 0xffff0000, v81
	v_pk_mul_f32 v[12:13], v[14:15], v[12:13]
	s_nop 0
	v_pk_mul_f32 v[12:13], v[64:65], v[12:13]
	v_pk_mul_f32 v[64:65], v[66:67], v[0:1] op_sel_hi:[1,0]
	v_cvt_pk_bf16_f32 v12, v12, v13
	v_mul_f32_e32 v13, 0xbfb8aa3b, v6
	v_exp_f32_e32 v13, v13
	s_nop 0
	v_add_f32_e32 v13, 1.0, v13
	v_rcp_f32_e32 v14, v13
	v_mul_f32_e32 v13, 0xbfb8aa3b, v7
	v_exp_f32_e32 v13, v13
	s_nop 0
	v_add_f32_e32 v13, 1.0, v13
	v_rcp_f32_e32 v15, v13
	s_nop 0
	v_pk_mul_f32 v[6:7], v[14:15], v[6:7]
	s_nop 0
	v_pk_mul_f32 v[6:7], v[64:65], v[6:7]
	v_pk_mul_f32 v[64:65], v[68:69], v[0:1] op_sel_hi:[1,0]
	v_cvt_pk_bf16_f32 v13, v6, v7
	v_lshl_add_u64 v[6:7], v[10:11], 0, s[10:11]
	v_add_co_u32_e32 v10, vcc, s3, v10
	s_nop 1
	v_addc_co_u32_e32 v11, vcc, 0, v11, vcc
	global_store_dwordx2 v[10:11], v[12:13], off offset:1024
	s_waitcnt vmcnt(15)
	v_lshlrev_b32_e32 v12, 16, v82
	v_and_b32_e32 v13, 0xffff0000, v82
	v_mul_f32_e32 v10, 0xbfb8aa3b, v12
	v_exp_f32_e32 v10, v10
	s_nop 0
	v_add_f32_e32 v10, 1.0, v10
	v_rcp_f32_e32 v14, v10
	v_mul_f32_e32 v10, 0xbfb8aa3b, v13
	v_exp_f32_e32 v10, v10
	s_nop 0
	v_add_f32_e32 v10, 1.0, v10
	v_rcp_f32_e32 v15, v10
	s_nop 0
	v_pk_mul_f32 v[12:13], v[14:15], v[12:13]
	s_nop 0
	v_pk_mul_f32 v[12:13], v[64:65], v[12:13]
	v_pk_mul_f32 v[64:65], v[70:71], v[0:1] op_sel_hi:[1,0]
	v_cvt_pk_bf16_f32 v10, v12, v13
	v_lshlrev_b32_e32 v12, 16, v83
	v_and_b32_e32 v13, 0xffff0000, v83
	v_mul_f32_e32 v11, 0xbfb8aa3b, v12
	v_exp_f32_e32 v11, v11
	s_nop 0
	v_add_f32_e32 v11, 1.0, v11
	v_rcp_f32_e32 v14, v11
	v_mul_f32_e32 v11, 0xbfb8aa3b, v13
	v_exp_f32_e32 v11, v11
	s_nop 0
	v_add_f32_e32 v11, 1.0, v11
	v_rcp_f32_e32 v15, v11
	s_nop 0
	v_pk_mul_f32 v[12:13], v[14:15], v[12:13]
	s_nop 0
	v_pk_mul_f32 v[12:13], v[64:65], v[12:13]
	v_pk_mul_f32 v[64:65], v[72:73], v[0:1] op_sel_hi:[1,0]
	v_cvt_pk_bf16_f32 v11, v12, v13
	global_store_dwordx2 v[6:7], v[10:11], off offset:16
	s_waitcnt vmcnt(15)
	v_lshlrev_b32_e32 v12, 16, v84
	v_and_b32_e32 v13, 0xffff0000, v84
	v_mul_f32_e32 v10, 0xbfb8aa3b, v12
	v_exp_f32_e32 v10, v10
	s_nop 0
	v_add_f32_e32 v10, 1.0, v10
	v_rcp_f32_e32 v14, v10
	v_mul_f32_e32 v10, 0xbfb8aa3b, v13
	v_exp_f32_e32 v10, v10
	s_nop 0
	v_add_f32_e32 v10, 1.0, v10
	v_rcp_f32_e32 v15, v10
	s_nop 0
	v_pk_mul_f32 v[12:13], v[14:15], v[12:13]
	s_nop 0
	v_pk_mul_f32 v[12:13], v[64:65], v[12:13]
	v_pk_mul_f32 v[64:65], v[74:75], v[0:1] op_sel_hi:[1,0]
	v_cvt_pk_bf16_f32 v10, v12, v13
	v_lshlrev_b32_e32 v12, 16, v85
	v_and_b32_e32 v13, 0xffff0000, v85
	v_mul_f32_e32 v11, 0xbfb8aa3b, v12
	v_exp_f32_e32 v11, v11
	s_nop 0
	v_add_f32_e32 v11, 1.0, v11
	v_rcp_f32_e32 v14, v11
	v_mul_f32_e32 v11, 0xbfb8aa3b, v13
	v_exp_f32_e32 v11, v11
	s_nop 0
	v_add_f32_e32 v11, 1.0, v11
	v_rcp_f32_e32 v15, v11
	s_nop 0
	v_pk_mul_f32 v[12:13], v[14:15], v[12:13]
	s_nop 0
	v_pk_mul_f32 v[12:13], v[64:65], v[12:13]
	v_pk_mul_f32 v[64:65], v[76:77], v[0:1] op_sel_hi:[1,0]
	v_cvt_pk_bf16_f32 v11, v12, v13
	global_store_dwordx2 v[6:7], v[10:11], off offset:32
	s_waitcnt vmcnt(15)
; DI float silu(float x) { return x * __builtin_amdgcn_rcpf(1.f + __expf(-x)); }
; DI u32x2 pk4(f32x4 v) { return u32x2{pk2(v[0], v[1]), pk2(v[2], v[3])}; }
; DI f32x4 unpk4(u32x2 u) { return f32x4{__uint_as_float(u[0] << 16), __uint_as_float(u[0] & 0xffff0000u), __uint_as_float(u[1] << 16), __uint_as_float(u[1] & 0xffff0000u)}; }
; DI void attn_item(const Ctx& c, int item, bf16* lds) {
;     ...
;     const float inv = 1.f / xhalf_sum(lsum[qs]);
;     ...
; #pragma unroll
;     for (int vt = 0; vt < 2; ++vt)
; #pragma unroll
;       for (int g = 0; g < 4; ++g) {
;         const int vd = 32 * vt + 8 * g + 4 * hh;
;         const f32x4 g4 = unpk4(*(const u32x2*)(mg + vd));
;         f32x4 o = {ot[qs][vt][4 * g] * inv * silu(g4[0]), ot[qs][vt][4 * g + 1] * inv * silu(g4[1]), ot[qs][vt][4 * g + 2] * inv * silu(g4[2]), ot[qs][vt][4 * g + 3] * inv * silu(g4[3])};
;         *(u32x2*)(dst + vd) = pk4(o);
;       }
	v_lshlrev_b32_e32 v12, 16, v86
	v_and_b32_e32 v13, 0xffff0000, v86
	v_mul_f32_e32 v10, 0xbfb8aa3b, v12
	v_exp_f32_e32 v10, v10
	s_nop 0
	v_add_f32_e32 v10, 1.0, v10
	v_rcp_f32_e32 v14, v10
	v_mul_f32_e32 v10, 0xbfb8aa3b, v13
	v_exp_f32_e32 v10, v10
	s_nop 0
	v_add_f32_e32 v10, 1.0, v10
	v_rcp_f32_e32 v15, v10
	s_nop 0
	v_pk_mul_f32 v[12:13], v[14:15], v[12:13]
	s_nop 0
	v_pk_mul_f32 v[12:13], v[64:65], v[12:13]
	v_pk_mul_f32 v[64:65], v[78:79], v[0:1] op_sel_hi:[1,0]
	v_cvt_pk_bf16_f32 v10, v12, v13
	v_lshlrev_b32_e32 v12, 16, v87
	v_and_b32_e32 v13, 0xffff0000, v87
	v_mul_f32_e32 v11, 0xbfb8aa3b, v12
	v_exp_f32_e32 v11, v11
	s_nop 0
	v_add_f32_e32 v11, 1.0, v11
	v_rcp_f32_e32 v14, v11
	v_mul_f32_e32 v11, 0xbfb8aa3b, v13
	v_exp_f32_e32 v11, v11
	s_nop 0
	v_add_f32_e32 v11, 1.0, v11
	v_rcp_f32_e32 v15, v11
	s_nop 0
	v_pk_mul_f32 v[12:13], v[14:15], v[12:13]
	s_nop 0
	v_pk_mul_f32 v[12:13], v[64:65], v[12:13]
	s_nop 0
	v_cvt_pk_bf16_f32 v11, v12, v13
	global_store_dwordx2 v[6:7], v[10:11], off offset:48
	s_waitcnt vmcnt(15)
	v_lshlrev_b32_e32 v12, 16, v88
	v_and_b32_e32 v13, 0xffff0000, v88
	v_mul_f32_e32 v10, 0xbfb8aa3b, v12
	v_exp_f32_e32 v10, v10
	s_nop 0
	v_add_f32_e32 v10, 1.0, v10
	v_rcp_f32_e32 v14, v10
	v_mul_f32_e32 v10, 0xbfb8aa3b, v13
	v_exp_f32_e32 v10, v10
	s_nop 0
	v_add_f32_e32 v10, 1.0, v10
	v_rcp_f32_e32 v15, v10
	s_nop 0
	v_pk_mul_f32 v[12:13], v[14:15], v[12:13]
	s_nop 0
	v_pk_mul_f32 v[12:13], v[48:49], v[12:13]
	v_pk_mul_f32 v[48:49], v[50:51], v[0:1] op_sel_hi:[1,0]
	v_cvt_pk_bf16_f32 v10, v12, v13
	v_lshlrev_b32_e32 v12, 16, v89
	v_and_b32_e32 v13, 0xffff0000, v89
	v_mul_f32_e32 v11, 0xbfb8aa3b, v12
	v_exp_f32_e32 v11, v11
	s_nop 0
	v_add_f32_e32 v11, 1.0, v11
	v_rcp_f32_e32 v14, v11
	v_mul_f32_e32 v11, 0xbfb8aa3b, v13
	v_exp_f32_e32 v11, v11
	s_nop 0
	v_add_f32_e32 v11, 1.0, v11
	v_rcp_f32_e32 v15, v11
	s_nop 0
	v_pk_mul_f32 v[12:13], v[14:15], v[12:13]
	s_nop 0
	v_pk_mul_f32 v[12:13], v[48:49], v[12:13]
	v_pk_mul_f32 v[48:49], v[52:53], v[0:1] op_sel_hi:[1,0]
	v_cvt_pk_bf16_f32 v11, v12, v13
	global_store_dwordx2 v[6:7], v[10:11], off offset:64
	s_waitcnt vmcnt(15)
	v_lshlrev_b32_e32 v12, 16, v90
	v_and_b32_e32 v13, 0xffff0000, v90
	v_mul_f32_e32 v10, 0xbfb8aa3b, v12
	v_exp_f32_e32 v10, v10
	s_nop 0
	v_add_f32_e32 v10, 1.0, v10
	v_rcp_f32_e32 v14, v10
	v_mul_f32_e32 v10, 0xbfb8aa3b, v13
	v_exp_f32_e32 v10, v10
	s_nop 0
	v_add_f32_e32 v10, 1.0, v10
	v_rcp_f32_e32 v15, v10
	s_nop 0
	v_pk_mul_f32 v[12:13], v[14:15], v[12:13]
	s_nop 0
	v_pk_mul_f32 v[12:13], v[48:49], v[12:13]
	v_pk_mul_f32 v[48:49], v[54:55], v[0:1] op_sel_hi:[1,0]
	v_cvt_pk_bf16_f32 v10, v12, v13
	v_lshlrev_b32_e32 v12, 16, v91
	v_and_b32_e32 v13, 0xffff0000, v91
	v_mul_f32_e32 v11, 0xbfb8aa3b, v12
	v_exp_f32_e32 v11, v11
	s_nop 0
	v_add_f32_e32 v11, 1.0, v11
	v_rcp_f32_e32 v14, v11
	v_mul_f32_e32 v11, 0xbfb8aa3b, v13
	v_exp_f32_e32 v11, v11
	s_nop 0
	v_add_f32_e32 v11, 1.0, v11
	v_rcp_f32_e32 v15, v11
	s_nop 0
	v_pk_mul_f32 v[12:13], v[14:15], v[12:13]
	s_nop 0
	v_pk_mul_f32 v[12:13], v[48:49], v[12:13]
	v_pk_mul_f32 v[48:49], v[56:57], v[0:1] op_sel_hi:[1,0]
	v_cvt_pk_bf16_f32 v11, v12, v13
	global_store_dwordx2 v[6:7], v[10:11], off offset:80
	s_waitcnt vmcnt(15)
	v_lshlrev_b32_e32 v12, 16, v92
	v_and_b32_e32 v13, 0xffff0000, v92
	v_mul_f32_e32 v10, 0xbfb8aa3b, v12
	v_exp_f32_e32 v10, v10
	s_nop 0
	v_add_f32_e32 v10, 1.0, v10
	v_rcp_f32_e32 v14, v10
	v_mul_f32_e32 v10, 0xbfb8aa3b, v13
	v_exp_f32_e32 v10, v10
	s_nop 0
	v_add_f32_e32 v10, 1.0, v10
	v_rcp_f32_e32 v15, v10
	s_nop 0
	v_pk_mul_f32 v[12:13], v[14:15], v[12:13]
	s_nop 0
	v_pk_mul_f32 v[12:13], v[48:49], v[12:13]
	v_pk_mul_f32 v[48:49], v[58:59], v[0:1] op_sel_hi:[1,0]
	v_cvt_pk_bf16_f32 v10, v12, v13
	v_lshlrev_b32_e32 v12, 16, v93
	v_and_b32_e32 v13, 0xffff0000, v93
	v_mul_f32_e32 v11, 0xbfb8aa3b, v12
	v_exp_f32_e32 v11, v11
	s_nop 0
	v_add_f32_e32 v11, 1.0, v11
	v_rcp_f32_e32 v14, v11
	v_mul_f32_e32 v11, 0xbfb8aa3b, v13
	v_exp_f32_e32 v11, v11
	s_nop 0
	v_add_f32_e32 v11, 1.0, v11
	v_rcp_f32_e32 v15, v11
	s_nop 0
	v_pk_mul_f32 v[12:13], v[14:15], v[12:13]
	s_nop 0
	v_pk_mul_f32 v[12:13], v[48:49], v[12:13]
	v_pk_mul_f32 v[14:15], v[60:61], v[0:1] op_sel_hi:[1,0]
	v_cvt_pk_bf16_f32 v11, v12, v13
	global_store_dwordx2 v[6:7], v[10:11], off offset:96
	s_waitcnt vmcnt(15)
	v_lshlrev_b32_e32 v10, 16, v94
	v_and_b32_e32 v11, 0xffff0000, v94
	v_mul_f32_e32 v4, 0xbfb8aa3b, v10
	v_exp_f32_e32 v4, v4
	s_nop 0
	v_add_f32_e32 v4, 1.0, v4
	v_rcp_f32_e32 v12, v4
	v_mul_f32_e32 v4, 0xbfb8aa3b, v11
	v_exp_f32_e32 v4, v4
	s_nop 0
	v_add_f32_e32 v4, 1.0, v4
	v_rcp_f32_e32 v13, v4
	s_nop 0
	v_pk_mul_f32 v[10:11], v[12:13], v[10:11]
	s_nop 0
	v_pk_mul_f32 v[10:11], v[14:15], v[10:11]
	v_pk_mul_f32 v[14:15], v[62:63], v[0:1] op_sel_hi:[1,0]
	v_cvt_pk_bf16_f32 v4, v10, v11
	v_lshlrev_b32_e32 v10, 16, v95
	v_and_b32_e32 v11, 0xffff0000, v95
	v_mul_f32_e32 v5, 0xbfb8aa3b, v10
	v_mul_f32_e32 v0, 0xbfb8aa3b, v11
	v_exp_f32_e32 v5, v5
	v_exp_f32_e32 v0, v0
	v_add_f32_e32 v5, 1.0, v5
	v_add_f32_e32 v0, 1.0, v0
	v_rcp_f32_e32 v12, v5
	v_rcp_f32_e32 v13, v0
	v_mov_b32_e32 v0, v8
	s_nop 1
	v_permlane32_swap_b32_e32 v8, v0
	v_pk_mul_f32 v[10:11], v[12:13], v[10:11]
	v_add_f32_e32 v0, v8, v0
	v_pk_mul_f32 v[10:11], v[14:15], v[10:11]
	s_nop 0
	v_cvt_pk_bf16_f32 v5, v10, v11
	global_store_dwordx2 v[6:7], v[4:5], off offset:112
	v_div_scale_f32 v4, s[0:1], v0, v0, 1.0
	v_rcp_f32_e32 v5, v4
	s_nop 0
	v_fma_f32 v6, -v4, v5, 1.0
	v_fmac_f32_e32 v5, v6, v5
	v_div_scale_f32 v6, vcc, 1.0, v0, 1.0
	v_mul_f32_e32 v7, v6, v5
	v_fma_f32 v8, -v4, v7, v6
	v_fmac_f32_e32 v7, v8, v5
	v_fma_f32 v4, -v4, v7, v6
	v_or_b32_e32 v6, 32, v9
	v_div_fmas_f32 v4, v4, v5, v7
	v_mad_i64_i32 v[2:3], s[0:1], v6, s78, v[2:3]
	v_div_fixup_f32 v0, v4, v0, 1.0
	v_lshl_add_u64 v[4:5], v[2:3], 0, s[4:5]
	v_mad_i64_i32 v[2:3], s[0:1], v6, s2, v[2:3]
	v_lshl_add_u64 v[6:7], v[4:5], 0, v[156:157]
	v_lshl_add_u64 v[4:5], v[6:7], 0, s[8:9]
	v_add_co_u32_e32 v6, vcc, s81, v6
	v_pk_mul_f32 v[12:13], v[32:33], v[0:1] op_sel_hi:[1,0]
	s_nop 0
	v_addc_co_u32_e32 v7, vcc, 0, v7, vcc
	v_lshl_add_u64 v[2:3], v[2:3], 0, s[4:5]
	s_waitcnt vmcnt(15)
; DI float silu(float x) { return x * __builtin_amdgcn_rcpf(1.f + __expf(-x)); }
; DI u32x2 pk4(f32x4 v) { return u32x2{pk2(v[0], v[1]), pk2(v[2], v[3])}; }
; DI f32x4 unpk4(u32x2 u) { return f32x4{__uint_as_float(u[0] << 16), __uint_as_float(u[0] & 0xffff0000u), __uint_as_float(u[1] << 16), __uint_as_float(u[1] & 0xffff0000u)}; }
; DI void attn_item(const Ctx& c, int item, bf16* lds) {
;     ...
; #pragma unroll
;     for (int vt = 0; vt < 2; ++vt)
; #pragma unroll
;       for (int g = 0; g < 4; ++g) {
;         const int vd = 32 * vt + 8 * g + 4 * hh;
;         const f32x4 g4 = unpk4(*(const u32x2*)(mg + vd));
;         f32x4 o = {ot[qs][vt][4 * g] * inv * silu(g4[0]), ot[qs][vt][4 * g + 1] * inv * silu(g4[1]), ot[qs][vt][4 * g + 2] * inv * silu(g4[2]), ot[qs][vt][4 * g + 3] * inv * silu(g4[3])};
;         *(u32x2*)(dst + vd) = pk4(o);
;       }
	v_lshlrev_b32_e32 v8, 16, v96
	v_and_b32_e32 v9, 0xffff0000, v96
	v_mul_f32_e32 v6, 0xbfb8aa3b, v8
	v_exp_f32_e32 v6, v6
	s_nop 0
	v_add_f32_e32 v6, 1.0, v6
	v_rcp_f32_e32 v10, v6
	v_mul_f32_e32 v6, 0xbfb8aa3b, v9
	v_exp_f32_e32 v6, v6
	s_nop 0
	v_add_f32_e32 v6, 1.0, v6
	v_rcp_f32_e32 v11, v6
	s_nop 0
	v_pk_mul_f32 v[8:9], v[10:11], v[8:9]
	s_nop 0
	v_pk_mul_f32 v[8:9], v[12:13], v[8:9]
	v_pk_mul_f32 v[12:13], v[34:35], v[0:1] op_sel_hi:[1,0]
	v_cvt_pk_bf16_f32 v6, v8, v9
	v_lshlrev_b32_e32 v8, 16, v97
	v_and_b32_e32 v9, 0xffff0000, v97
	v_mul_f32_e32 v7, 0xbfb8aa3b, v8
	v_exp_f32_e32 v7, v7
	s_nop 0
	v_add_f32_e32 v7, 1.0, v7
	v_rcp_f32_e32 v10, v7
	v_mul_f32_e32 v7, 0xbfb8aa3b, v9
	v_exp_f32_e32 v7, v7
	s_nop 0
	v_add_f32_e32 v7, 1.0, v7
	v_rcp_f32_e32 v11, v7
	s_nop 0
	v_pk_mul_f32 v[8:9], v[10:11], v[8:9]
	s_nop 0
	v_pk_mul_f32 v[8:9], v[12:13], v[8:9]
	v_pk_mul_f32 v[12:13], v[36:37], v[0:1] op_sel_hi:[1,0]
	v_cvt_pk_bf16_f32 v7, v8, v9
	v_lshl_add_u64 v[8:9], v[2:3], 0, v[156:157]
	v_lshl_add_u64 v[2:3], v[8:9], 0, s[10:11]
	v_add_co_u32_e32 v8, vcc, s3, v8
	s_nop 1
	v_addc_co_u32_e32 v9, vcc, 0, v9, vcc
	global_store_dwordx2 v[8:9], v[6:7], off offset:1024
	s_waitcnt vmcnt(15)
	v_lshlrev_b32_e32 v8, 16, v98
	v_and_b32_e32 v9, 0xffff0000, v98
	v_mul_f32_e32 v6, 0xbfb8aa3b, v8
	v_exp_f32_e32 v6, v6
	s_nop 0
	v_add_f32_e32 v6, 1.0, v6
	v_rcp_f32_e32 v10, v6
	v_mul_f32_e32 v6, 0xbfb8aa3b, v9
	v_exp_f32_e32 v6, v6
	s_nop 0
	v_add_f32_e32 v6, 1.0, v6
	v_rcp_f32_e32 v11, v6
	s_nop 0
	v_pk_mul_f32 v[8:9], v[10:11], v[8:9]
	s_nop 0
	v_pk_mul_f32 v[8:9], v[12:13], v[8:9]
	v_pk_mul_f32 v[12:13], v[38:39], v[0:1] op_sel_hi:[1,0]
	v_cvt_pk_bf16_f32 v6, v8, v9
	v_lshlrev_b32_e32 v8, 16, v99
	v_and_b32_e32 v9, 0xffff0000, v99
	v_mul_f32_e32 v7, 0xbfb8aa3b, v8
	v_exp_f32_e32 v7, v7
	s_nop 0
	v_add_f32_e32 v7, 1.0, v7
	v_rcp_f32_e32 v10, v7
	v_mul_f32_e32 v7, 0xbfb8aa3b, v9
	v_exp_f32_e32 v7, v7
	s_nop 0
	v_add_f32_e32 v7, 1.0, v7
	v_rcp_f32_e32 v11, v7
	s_nop 0
	v_pk_mul_f32 v[8:9], v[10:11], v[8:9]
	s_nop 0
	v_pk_mul_f32 v[8:9], v[12:13], v[8:9]
	v_pk_mul_f32 v[12:13], v[40:41], v[0:1] op_sel_hi:[1,0]
	v_cvt_pk_bf16_f32 v7, v8, v9
	global_store_dwordx2 v[2:3], v[6:7], off offset:16
	s_waitcnt vmcnt(15)
	v_lshlrev_b32_e32 v8, 16, v100
	v_and_b32_e32 v9, 0xffff0000, v100
	v_mul_f32_e32 v6, 0xbfb8aa3b, v8
	v_exp_f32_e32 v6, v6
	s_nop 0
	v_add_f32_e32 v6, 1.0, v6
	v_rcp_f32_e32 v10, v6
	v_mul_f32_e32 v6, 0xbfb8aa3b, v9
	v_exp_f32_e32 v6, v6
	s_nop 0
	v_add_f32_e32 v6, 1.0, v6
	v_rcp_f32_e32 v11, v6
	s_nop 0
	v_pk_mul_f32 v[8:9], v[10:11], v[8:9]
	s_nop 0
	v_pk_mul_f32 v[8:9], v[12:13], v[8:9]
	v_pk_mul_f32 v[12:13], v[42:43], v[0:1] op_sel_hi:[1,0]
	v_cvt_pk_bf16_f32 v6, v8, v9
	v_lshlrev_b32_e32 v8, 16, v101
	v_and_b32_e32 v9, 0xffff0000, v101
	v_mul_f32_e32 v7, 0xbfb8aa3b, v8
	v_exp_f32_e32 v7, v7
	s_nop 0
	v_add_f32_e32 v7, 1.0, v7
	v_rcp_f32_e32 v10, v7
	v_mul_f32_e32 v7, 0xbfb8aa3b, v9
	v_exp_f32_e32 v7, v7
	s_nop 0
	v_add_f32_e32 v7, 1.0, v7
	v_rcp_f32_e32 v11, v7
	s_nop 0
	v_pk_mul_f32 v[8:9], v[10:11], v[8:9]
	s_nop 0
	v_pk_mul_f32 v[8:9], v[12:13], v[8:9]
	v_pk_mul_f32 v[12:13], v[44:45], v[0:1] op_sel_hi:[1,0]
	v_cvt_pk_bf16_f32 v7, v8, v9
	global_store_dwordx2 v[2:3], v[6:7], off offset:32
	s_waitcnt vmcnt(15)
	v_lshlrev_b32_e32 v8, 16, v102
	v_and_b32_e32 v9, 0xffff0000, v102
	v_mul_f32_e32 v6, 0xbfb8aa3b, v8
	v_exp_f32_e32 v6, v6
	s_nop 0
	v_add_f32_e32 v6, 1.0, v6
	v_rcp_f32_e32 v10, v6
	v_mul_f32_e32 v6, 0xbfb8aa3b, v9
	v_exp_f32_e32 v6, v6
	s_nop 0
	v_add_f32_e32 v6, 1.0, v6
	v_rcp_f32_e32 v11, v6
	s_nop 0
	v_pk_mul_f32 v[8:9], v[10:11], v[8:9]
	s_nop 0
	v_pk_mul_f32 v[8:9], v[12:13], v[8:9]
	v_pk_mul_f32 v[12:13], v[46:47], v[0:1] op_sel_hi:[1,0]
	v_cvt_pk_bf16_f32 v6, v8, v9
	v_lshlrev_b32_e32 v8, 16, v103
	v_and_b32_e32 v9, 0xffff0000, v103
	v_mul_f32_e32 v7, 0xbfb8aa3b, v8
	v_exp_f32_e32 v7, v7
	s_nop 0
	v_add_f32_e32 v7, 1.0, v7
	v_rcp_f32_e32 v10, v7
	v_mul_f32_e32 v7, 0xbfb8aa3b, v9
	v_exp_f32_e32 v7, v7
	s_nop 0
	v_add_f32_e32 v7, 1.0, v7
	v_rcp_f32_e32 v11, v7
	s_nop 0
	v_pk_mul_f32 v[8:9], v[10:11], v[8:9]
	s_nop 0
	v_pk_mul_f32 v[8:9], v[12:13], v[8:9]
	v_pk_mul_f32 v[12:13], v[16:17], v[0:1] op_sel_hi:[1,0]
	v_cvt_pk_bf16_f32 v7, v8, v9
	global_store_dwordx2 v[2:3], v[6:7], off offset:48
	s_waitcnt vmcnt(15)
; DI float silu(float x) { return x * __builtin_amdgcn_rcpf(1.f + __expf(-x)); }
;   DI bf16* G() const { return (bf16*)(p.ws + WS_G); }
; DI u32x2 pk4(f32x4 v) { return u32x2{pk2(v[0], v[1]), pk2(v[2], v[3])}; }
; DI f32x4 unpk4(u32x2 u) { return f32x4{__uint_as_float(u[0] << 16), __uint_as_float(u[0] & 0xffff0000u), __uint_as_float(u[1] << 16), __uint_as_float(u[1] & 0xffff0000u)}; }
; template <class F>
; DI void xcd_items(int total, const F& f) {
;   const int G = gridDim.x;
;   if ((G & 7) == 0 && (total & 7) == 0) {
;     const int x = blockIdx.x & 7, j = blockIdx.x >> 3, per = total >> 3, gl = G >> 3;
;     for (int q = j; q < per; q += gl) f(x * per + q);
;   } else {
;     for (int t = blockIdx.x; t < total; t += G) f(t);
;   }
; DI void attn_item(const Ctx& c, int item, bf16* lds) {
;     ...
; #pragma unroll
;     for (int vt = 0; vt < 2; ++vt)
; #pragma unroll
;       for (int g = 0; g < 4; ++g) {
;         const int vd = 32 * vt + 8 * g + 4 * hh;
;         const f32x4 g4 = unpk4(*(const u32x2*)(mg + vd));
;         f32x4 o = {ot[qs][vt][4 * g] * inv * silu(g4[0]), ot[qs][vt][4 * g + 1] * inv * silu(g4[1]), ot[qs][vt][4 * g + 2] * inv * silu(g4[2]), ot[qs][vt][4 * g + 3] * inv * silu(g4[3])};
;         *(u32x2*)(dst + vd) = pk4(o);
;       }
;   }
	v_lshlrev_b32_e32 v8, 16, v104
	v_and_b32_e32 v9, 0xffff0000, v104
	v_mul_f32_e32 v6, 0xbfb8aa3b, v8
	v_exp_f32_e32 v6, v6
	s_nop 0
	v_add_f32_e32 v6, 1.0, v6
	v_rcp_f32_e32 v10, v6
	v_mul_f32_e32 v6, 0xbfb8aa3b, v9
	v_exp_f32_e32 v6, v6
	s_nop 0
	v_add_f32_e32 v6, 1.0, v6
	v_rcp_f32_e32 v11, v6
	s_nop 0
	v_pk_mul_f32 v[8:9], v[10:11], v[8:9]
	s_nop 0
	v_pk_mul_f32 v[8:9], v[12:13], v[8:9]
	v_pk_mul_f32 v[12:13], v[18:19], v[0:1] op_sel_hi:[1,0]
	v_cvt_pk_bf16_f32 v6, v8, v9
	v_lshlrev_b32_e32 v8, 16, v105
	v_and_b32_e32 v9, 0xffff0000, v105
	v_mul_f32_e32 v7, 0xbfb8aa3b, v8
	v_exp_f32_e32 v7, v7
	s_nop 0
	v_add_f32_e32 v7, 1.0, v7
	v_rcp_f32_e32 v10, v7
	v_mul_f32_e32 v7, 0xbfb8aa3b, v9
	v_exp_f32_e32 v7, v7
	s_nop 0
	v_add_f32_e32 v7, 1.0, v7
	v_rcp_f32_e32 v11, v7
	s_nop 0
	v_pk_mul_f32 v[8:9], v[10:11], v[8:9]
	s_nop 0
	v_pk_mul_f32 v[8:9], v[12:13], v[8:9]
	v_pk_mul_f32 v[12:13], v[20:21], v[0:1] op_sel_hi:[1,0]
	v_cvt_pk_bf16_f32 v7, v8, v9
	global_store_dwordx2 v[2:3], v[6:7], off offset:64
	s_waitcnt vmcnt(15)
	v_lshlrev_b32_e32 v8, 16, v106
	v_and_b32_e32 v9, 0xffff0000, v106
	v_mul_f32_e32 v6, 0xbfb8aa3b, v8
	v_exp_f32_e32 v6, v6
	s_nop 0
	v_add_f32_e32 v6, 1.0, v6
	v_rcp_f32_e32 v10, v6
	v_mul_f32_e32 v6, 0xbfb8aa3b, v9
	v_exp_f32_e32 v6, v6
	s_nop 0
	v_add_f32_e32 v6, 1.0, v6
	v_rcp_f32_e32 v11, v6
	s_nop 0
	v_pk_mul_f32 v[8:9], v[10:11], v[8:9]
	s_nop 0
	v_pk_mul_f32 v[8:9], v[12:13], v[8:9]
	v_pk_mul_f32 v[12:13], v[22:23], v[0:1] op_sel_hi:[1,0]
	v_cvt_pk_bf16_f32 v6, v8, v9
	v_lshlrev_b32_e32 v8, 16, v107
	v_and_b32_e32 v9, 0xffff0000, v107
	v_mul_f32_e32 v7, 0xbfb8aa3b, v8
	v_exp_f32_e32 v7, v7
	s_nop 0
	v_add_f32_e32 v7, 1.0, v7
	v_rcp_f32_e32 v10, v7
	v_mul_f32_e32 v7, 0xbfb8aa3b, v9
	v_exp_f32_e32 v7, v7
	s_nop 0
	v_add_f32_e32 v7, 1.0, v7
	v_rcp_f32_e32 v11, v7
	s_nop 0
	v_pk_mul_f32 v[8:9], v[10:11], v[8:9]
	s_nop 0
	v_pk_mul_f32 v[8:9], v[12:13], v[8:9]
	v_pk_mul_f32 v[12:13], v[24:25], v[0:1] op_sel_hi:[1,0]
	v_cvt_pk_bf16_f32 v7, v8, v9
	global_store_dwordx2 v[2:3], v[6:7], off offset:80
	s_waitcnt vmcnt(15)
	v_lshlrev_b32_e32 v8, 16, v108
	v_and_b32_e32 v9, 0xffff0000, v108
	v_mul_f32_e32 v6, 0xbfb8aa3b, v8
	v_exp_f32_e32 v6, v6
	s_nop 0
	v_add_f32_e32 v6, 1.0, v6
	v_rcp_f32_e32 v10, v6
	v_mul_f32_e32 v6, 0xbfb8aa3b, v9
	v_exp_f32_e32 v6, v6
	s_nop 0
	v_add_f32_e32 v6, 1.0, v6
	v_rcp_f32_e32 v11, v6
	s_nop 0
	v_pk_mul_f32 v[8:9], v[10:11], v[8:9]
	s_nop 0
	v_pk_mul_f32 v[8:9], v[12:13], v[8:9]
	v_pk_mul_f32 v[12:13], v[26:27], v[0:1] op_sel_hi:[1,0]
	v_cvt_pk_bf16_f32 v6, v8, v9
	v_lshlrev_b32_e32 v8, 16, v109
	v_and_b32_e32 v9, 0xffff0000, v109
	v_mul_f32_e32 v7, 0xbfb8aa3b, v8
	v_exp_f32_e32 v7, v7
	s_nop 0
	v_add_f32_e32 v7, 1.0, v7
	v_rcp_f32_e32 v10, v7
	v_mul_f32_e32 v7, 0xbfb8aa3b, v9
	v_exp_f32_e32 v7, v7
	s_nop 0
	v_add_f32_e32 v7, 1.0, v7
	v_rcp_f32_e32 v11, v7
	s_nop 0
	v_pk_mul_f32 v[8:9], v[10:11], v[8:9]
	s_nop 0
	v_pk_mul_f32 v[8:9], v[12:13], v[8:9]
	v_pk_mul_f32 v[10:11], v[28:29], v[0:1] op_sel_hi:[1,0]
	v_cvt_pk_bf16_f32 v7, v8, v9
	global_store_dwordx2 v[2:3], v[6:7], off offset:96
	s_waitcnt vmcnt(15)
	v_lshlrev_b32_e32 v6, 16, v110
	v_and_b32_e32 v7, 0xffff0000, v110
	v_mul_f32_e32 v4, 0xbfb8aa3b, v6
	v_exp_f32_e32 v4, v4
	s_nop 0
	v_add_f32_e32 v4, 1.0, v4
	v_rcp_f32_e32 v8, v4
	v_mul_f32_e32 v4, 0xbfb8aa3b, v7
	v_exp_f32_e32 v4, v4
	s_nop 0
	v_add_f32_e32 v4, 1.0, v4
	v_rcp_f32_e32 v9, v4
	s_nop 0
	v_pk_mul_f32 v[6:7], v[8:9], v[6:7]
	s_nop 0
	v_pk_mul_f32 v[6:7], v[10:11], v[6:7]
	v_pk_mul_f32 v[10:11], v[30:31], v[0:1] op_sel_hi:[1,0]
	v_cvt_pk_bf16_f32 v4, v6, v7
	v_lshlrev_b32_e32 v6, 16, v111
	v_and_b32_e32 v7, 0xffff0000, v111
	v_mul_f32_e32 v5, 0xbfb8aa3b, v6
	v_mul_f32_e32 v0, 0xbfb8aa3b, v7
	v_exp_f32_e32 v5, v5
	v_exp_f32_e32 v0, v0
	v_add_f32_e32 v5, 1.0, v5
	v_add_f32_e32 v0, 1.0, v0
	v_rcp_f32_e32 v8, v5
	v_rcp_f32_e32 v9, v0
	s_nop 0
	v_pk_mul_f32 v[6:7], v[8:9], v[6:7]
	s_nop 0
	v_pk_mul_f32 v[6:7], v[10:11], v[6:7]
	s_nop 0
	v_cvt_pk_bf16_f32 v5, v6, v7
	global_store_dwordx2 v[2:3], v[4:5], off offset:112
	s_cbranch_scc1 .LBB0_804

; DI void attn_item(const Ctx& c, int item, bf16* lds) {
;     ...
;   const int ntile = nk >> 6;
;   for (int kt = 0; kt < ntile; ++kt) {
.Lattn_pre:
	v_readlane_b32 vcc_lo, v252, 32
	s_cmp_ge_u32 vcc_lo, 0x10000
	s_cbranch_scc0 .Lattn_noprio
	s_setprio 1

; #define MFMA32(a, b, c) __builtin_amdgcn_mfma_f32_32x32x16_bf16((a), (b), (c), 0, 0, 0)
; DI void attn_item(const Ctx& c, int item, bf16* lds) {
;     ...
;       float ps = 0.f;
; #pragma unroll
;       for (int sp = 0; sp < 4; ++sp) {
;         const int mt = sp >> 1, s2 = sp & 1;
;         float e[8];
; #pragma unroll
;         for (int j = 0; j < 8; ++j) { e[j] = __builtin_amdgcn_exp2f(st[mt][8 * s2 + j]); ps += e[j]; }
;         u32x4 pk;
;         pk[0] = pk2(e[0], e[1]); pk[1] = pk2(e[2], e[3]); pk[2] = pk2(e[4], e[5]); pk[3] = pk2(e[6], e[7]);
;         const bf16x8 pf = __builtin_bit_cast(bf16x8, pk);
; #pragma unroll
;         for (int vt = 0; vt < 2; ++vt) {
;           const bf16* vp = Vs + (32 * vt + r) * AV_LD + 32 * mt + 16 * s2 + 4 * hh;
;           const s16x4 lo = *(const s16x4*)(vp), hi = *(const s16x4*)(vp + 8);
;           const bf16x8 a = __builtin_shufflevector(lo, hi, 0, 1, 2, 3, 4, 5, 6, 7);
;           ot[qs][vt] = MFMA32(a, pf, ot[qs][vt]);
;         }
;       }
;       lsum[qs] += ps;
;     }
;   }
.Lattn_21_B_back:
	v_exp_f32_e32 v96, v96
	v_exp_f32_e32 v97, v97
	s_waitcnt lgkmcnt(5)
	v_mfma_f32_32x32x16_bf16 v[80:95], v[204:207], v[112:115], 0
	v_exp_f32_e32 v98, v98
	v_exp_f32_e32 v99, v99
	v_exp_f32_e32 v100, v100
	v_exp_f32_e32 v101, v101
	s_waitcnt lgkmcnt(4)
	v_mfma_f32_32x32x16_bf16 v[80:95], v[208:211], v[116:119], v[80:95]
	v_exp_f32_e32 v102, v102
	v_exp_f32_e32 v103, v103
	v_add_f32_e32 v203, v203, v96
	v_add_f32_e32 v203, v203, v97
	v_add_f32_e32 v203, v203, v98
	s_waitcnt lgkmcnt(3)
	v_mfma_f32_32x32x16_bf16 v[80:95], v[212:215], v[120:123], v[80:95]
	v_add_f32_e32 v203, v203, v99
	v_add_f32_e32 v203, v203, v100
	v_add_f32_e32 v203, v203, v101
	v_add_f32_e32 v203, v203, v102
	v_add_f32_e32 v203, v203, v103
	v_cvt_pk_bf16_f32 v96, v96, v97
	v_cvt_pk_bf16_f32 v97, v98, v99
	s_waitcnt lgkmcnt(2)
	v_mfma_f32_32x32x16_bf16 v[80:95], v[216:219], v[124:127], v[80:95]
	v_cvt_pk_bf16_f32 v98, v100, v101
	v_cvt_pk_bf16_f32 v99, v102, v103
	v_exp_f32_e32 v104, v104
	v_exp_f32_e32 v105, v105
	v_exp_f32_e32 v106, v106
	s_waitcnt lgkmcnt(1)
	v_mfma_f32_32x32x16_bf16 v[80:95], v[220:223], v[128:131], v[80:95]
	v_exp_f32_e32 v107, v107
	v_exp_f32_e32 v108, v108
	v_exp_f32_e32 v109, v109
	v_exp_f32_e32 v110, v110
	s_waitcnt lgkmcnt(0)
	v_mfma_f32_32x32x16_bf16 v[80:95], v[224:227], v[132:135], v[80:95]
	v_exp_f32_e32 v111, v111
	v_add_f32_e32 v203, v203, v104
	v_add_f32_e32 v203, v203, v105
	v_add_f32_e32 v203, v203, v106
	v_add_f32_e32 v203, v203, v107
	v_add_f32_e32 v203, v203, v108
	s_add_i32 s1, s1, 1
	v_add_f32_e32 v203, v203, v109
	v_add_f32_e32 v203, v203, v110
	v_add_f32_e32 v203, v203, v111
	v_cvt_pk_bf16_f32 v104, v104, v105
	v_cvt_pk_bf16_f32 v105, v106, v107
	v_cvt_pk_bf16_f32 v106, v108, v109
	v_cvt_pk_bf16_f32 v107, v110, v111
	s_cmpk_lg_i32 s1, 0x84
	s_cbranch_scc1 .Lattn_loop
	v_mfma_f32_32x32x16_bf16 v[32:47], v[4:7], v[96:99], v[32:47]
	v_mfma_f32_32x32x16_bf16 v[16:31], v[8:11], v[96:99], v[16:31]
	v_mfma_f32_32x32x16_bf16 v[32:47], v[12:15], v[104:107], v[32:47]
	v_mfma_f32_32x32x16_bf16 v[16:31], v[192:195], v[104:107], v[16:31]
	v_mov_b32_e32 v8, v203
	s_setprio 0
	s_waitcnt vmcnt(0)
	s_branch .LBB0_820

; #define LDSR(dst, addr, off) asm volatile("ds_read_b128 %0, %1 offset:%2" : "=&v"(dst) : "v"(addr), "n"(off))
; #define LDSR(dst, addr, off) asm volatile("ds_read_b128 %0, %1 offset:%2" : "=&v"(dst) : "v"(addr), "n"(off))
; template <class AP, class BP, class Epi>
; DI void mfma_gemm_big_tile(const AP& aptr, const BP& bptr, int m0, int n0, int K, const Epi& epi, bf16* lds) {
;     ...
;   for (int ks = 0; ks < nk; ++ks) {
;     if (ks + 2 < nk) BG_ISSUE(nxt, ks + 2);
;     const unsigned sa = lbase + (unsigned)(cur * BG_STAGE * 2) + a_off, sb = lbase + (unsigned)(cur * BG_STAGE * 2) + b_off;
;     bf16x8 af[8], bfr[4];
;     LDSR(bfr[0], sb, 0); LDSR(bfr[1], sb, 1024); LDSR(bfr[2], sb, 2048); LDSR(bfr[3], sb, 3072);
;     LDSR(af[0], sa, 0); LDSR(af[1], sa, 1024); LDSR(af[2], sa, 2048); LDSR(af[3], sa, 3072);
;     LDSR(af[4], sa, 4096); LDSR(af[5], sa, 5120); LDSR(af[6], sa, 6144); LDSR(af[7], sa, 7168);
;     asm volatile("s_waitcnt lgkmcnt(0)" : "+v"(af[0]), "+v"(af[1]), "+v"(af[2]), "+v"(af[3]), "+v"(af[4]), "+v"(af[5]), "+v"(af[6]), "+v"(af[7]),
;                  "+v"(bfr[0]), "+v"(bfr[1]), "+v"(bfr[2]), "+v"(bfr[3]) : : "memory");
; #pragma unroll
;     for (int i = 0; i < 8; ++i)
; #pragma unroll
;       for (int j = 0; j < 4; ++j) acc[i][j] = __builtin_amdgcn_mfma_f32_16x16x32_bf16(bfr[j], af[i], acc[i][j], 0, 0, 0);
;     if (ks + 2 < nk) asm volatile("s_waitcnt vmcnt(6)\n\ts_barrier" ::: "memory");
;     else asm volatile("s_waitcnt vmcnt(0)\n\ts_barrier" ::: "memory");
;     cur = (cur == 2) ? 0 : cur + 1; nxt = (nxt == 2) ? 0 : nxt + 1;
;   }
.LBB0_1096:
	s_mul_i32 s10, s21, 0x6000
	v_add_u32_e32 v145, s10, v143
	v_add_u32_e32 v159, s10, v144
	ds_read_b128 v[146:149], v159 offset:0
	ds_read_b128 v[150:153], v159 offset:0x400
	ds_read_b128 v[154:157], v159 offset:0x800
	ds_read_b128 v[162:165], v159 offset:0xc00
	ds_read_b128 v[166:169], v145 offset:0
	ds_read_b128 v[182:185], v145 offset:0x400
	ds_read_b128 v[192:195], v145 offset:0x800
	ds_read_b128 v[196:199], v145 offset:0xc00
	ds_read_b128 v[200:203], v145 offset:0x1000
	ds_read_b128 v[204:207], v145 offset:0x1400
	ds_read_b128 v[208:211], v145 offset:0x1800
	ds_read_b128 v[212:215], v145 offset:0x1c00
	s_mov_b64 s[10:11], -1
	s_waitcnt lgkmcnt(7)
	s_and_b64 vcc, exec, s[8:9]
	v_mfma_f32_16x16x32_bf16 v[126:129], v[146:149], v[166:169], v[126:129]
	v_mfma_f32_16x16x32_bf16 v[122:125], v[150:153], v[166:169], v[122:125]
	v_mfma_f32_16x16x32_bf16 v[118:121], v[154:157], v[166:169], v[118:121]
	v_mfma_f32_16x16x32_bf16 v[114:117], v[162:165], v[166:169], v[114:117]
	s_waitcnt lgkmcnt(6)
	v_mfma_f32_16x16x32_bf16 v[110:113], v[146:149], v[182:185], v[110:113]
	v_mfma_f32_16x16x32_bf16 v[106:109], v[150:153], v[182:185], v[106:109]
	v_mfma_f32_16x16x32_bf16 v[102:105], v[154:157], v[182:185], v[102:105]
	v_mfma_f32_16x16x32_bf16 v[98:101], v[162:165], v[182:185], v[98:101]
	s_waitcnt lgkmcnt(5)
	v_mfma_f32_16x16x32_bf16 v[94:97], v[146:149], v[192:195], v[94:97]
	v_mfma_f32_16x16x32_bf16 v[90:93], v[150:153], v[192:195], v[90:93]
	v_mfma_f32_16x16x32_bf16 v[86:89], v[154:157], v[192:195], v[86:89]
	v_mfma_f32_16x16x32_bf16 v[82:85], v[162:165], v[192:195], v[82:85]
	s_waitcnt lgkmcnt(4)
	v_mfma_f32_16x16x32_bf16 v[78:81], v[146:149], v[196:199], v[78:81]
	v_mfma_f32_16x16x32_bf16 v[74:77], v[150:153], v[196:199], v[74:77]
	v_mfma_f32_16x16x32_bf16 v[70:73], v[154:157], v[196:199], v[70:73]
	v_mfma_f32_16x16x32_bf16 v[66:69], v[162:165], v[196:199], v[66:69]
	s_waitcnt lgkmcnt(3)
	v_mfma_f32_16x16x32_bf16 v[62:65], v[146:149], v[200:203], v[62:65]
	v_mfma_f32_16x16x32_bf16 v[58:61], v[150:153], v[200:203], v[58:61]
	v_mfma_f32_16x16x32_bf16 v[54:57], v[154:157], v[200:203], v[54:57]
	v_mfma_f32_16x16x32_bf16 v[50:53], v[162:165], v[200:203], v[50:53]
	s_waitcnt lgkmcnt(2)
	v_mfma_f32_16x16x32_bf16 v[46:49], v[146:149], v[204:207], v[46:49]
	v_mfma_f32_16x16x32_bf16 v[42:45], v[150:153], v[204:207], v[42:45]
	v_mfma_f32_16x16x32_bf16 v[38:41], v[154:157], v[204:207], v[38:41]
	v_mfma_f32_16x16x32_bf16 v[34:37], v[162:165], v[204:207], v[34:37]
	s_waitcnt lgkmcnt(1)
	v_mfma_f32_16x16x32_bf16 v[30:33], v[146:149], v[208:211], v[30:33]
	v_mfma_f32_16x16x32_bf16 v[26:29], v[150:153], v[208:211], v[26:29]
	v_mfma_f32_16x16x32_bf16 v[22:25], v[154:157], v[208:211], v[22:25]
	v_mfma_f32_16x16x32_bf16 v[18:21], v[162:165], v[208:211], v[18:21]
	s_waitcnt lgkmcnt(0)
	v_mfma_f32_16x16x32_bf16 v[14:17], v[146:149], v[212:215], v[14:17]
	v_mfma_f32_16x16x32_bf16 v[10:13], v[150:153], v[212:215], v[10:13]
	v_mfma_f32_16x16x32_bf16 v[6:9], v[154:157], v[212:215], v[6:9]
	v_mfma_f32_16x16x32_bf16 v[2:5], v[162:165], v[212:215], v[2:5]
	s_cbranch_vccz .LBB0_1098
	s_waitcnt vmcnt(0)
	s_barrier
	s_mov_b64 s[10:11], 0

;   DI float* MOD() const { return (float*)(p.ws + WS_MOD); }
; template <class AP, class BP, class Epi>
; DI void mfma_gemm_big_tile(const AP& aptr, const BP& bptr, int m0, int n0, int K, const Epi& epi, bf16* lds) {
;     ...
; #pragma unroll
;   for (int i = 0; i < 8; ++i)
; #pragma unroll
;     for (int j = 0; j < 4; ++j) epi(m0 + wm + 16 * i + l16, n0 + wn + 16 * j + 4 * lq, acc[i][j]);
;   DI void operator()(int m, int n, f32x4 v) const {
;     const bool lat = m < MLAT;
;     const size_t off = lat ? (size_t)m * D + n : (size_t)(m - MLAT) * D + n;
;     float* xp = (lat ? x_lat : x_ctx) + off;
;     const float4 xo = (l == 0) ? *(const float4*)((lat ? xin_lat : xin_ctx) + off) : *(const float4*)xp;
;     const float4 g = *(const float4*)(MOD + (l * 3 + mod_row(m)) * 3072 + 2048 + n);
;     *(float4*)xp = make_float4(ALPHA * xo.x + g.x * v[0], ALPHA * xo.y + g.y * v[1], ALPHA * xo.z + g.z * v[2], ALPHA * xo.w + g.w * v[3]);
;   }
.LBB0_1104:
.Lop_epi:
	v_and_b32_e32 v131, 15, v172
	v_bfe_u32 v130, v172, 4, 2
	s_add_i32 s0, s14, s19
	s_add_i32 s1, s15, s16
	v_add_u32_e32 v131, s0, v131
	v_lshl_add_u32 v130, v130, 2, s1
	v_lshlrev_b32_e32 v131, 12, v131
	v_lshlrev_b32_e32 v130, 2, v130
	v_add_u32_e32 v228, v131, v130
	v_add_u32_e32 v229, 0x10000, v228
	v_add_u32_e32 v230, 0x20000, v228
	v_add_u32_e32 v231, 0x30000, v228
	v_add_u32_e32 v232, 0x40000, v228
	v_add_u32_e32 v233, 0x50000, v228
	v_add_u32_e32 v234, 0x60000, v228
	v_add_u32_e32 v235, 0x70000, v228
	v_readlane_b32 s10, v252, 2
	v_readlane_b32 s11, v252, 3
	v_readlane_b32 s8, v252, 41
	v_readlane_b32 s9, v252, 42
	s_cmp_eq_u32 s86, 0
	s_cselect_b32 s8, s8, s10
	s_cselect_b32 s9, s9, s11
	s_lshr_b32 s0, s14, 13
	s_mul_i32 s1, s86, 3
	s_add_i32 s0, s0, s1
	s_mul_i32 s0, s0, 0x3000
	s_add_u32 s0, s0, 0x6000
	s_add_u32 s0, s88, s0
	s_addc_u32 s1, s89, 0
	global_load_dwordx4 v[236:239], v130, s[0:1] offset:0
	global_load_dwordx4 v[240:243], v130, s[0:1] offset:64
	global_load_dwordx4 v[244:247], v130, s[0:1] offset:128
	global_load_dwordx4 v[248:251], v130, s[0:1] offset:192
	global_load_dwordx4 v[192:195], v228, s[8:9] offset:0
	global_load_dwordx4 v[196:199], v228, s[8:9] offset:64
	global_load_dwordx4 v[200:203], v228, s[8:9] offset:128
	global_load_dwordx4 v[204:207], v228, s[8:9] offset:192
	global_load_dwordx4 v[208:211], v229, s[8:9] offset:0
	global_load_dwordx4 v[212:215], v229, s[8:9] offset:64
	global_load_dwordx4 v[216:219], v229, s[8:9] offset:128
	global_load_dwordx4 v[220:223], v229, s[8:9] offset:192
	global_load_dwordx4 v[132:135], v230, s[8:9] offset:0
	global_load_dwordx4 v[136:139], v230, s[8:9] offset:64
	global_load_dwordx4 v[140:143], v230, s[8:9] offset:128
	global_load_dwordx4 v[144:147], v230, s[8:9] offset:192
	global_load_dwordx4 v[148:151], v231, s[8:9] offset:0
	global_load_dwordx4 v[152:155], v231, s[8:9] offset:64
	global_load_dwordx4 v[164:167], v231, s[8:9] offset:128
	global_load_dwordx4 v[224:227], v231, s[8:9] offset:192
	s_waitcnt vmcnt(8)
	v_mul_f32_e32 v126, v126, v236
	v_mul_f32_e32 v127, v127, v237
	v_mul_f32_e32 v128, v128, v238
	v_mul_f32_e32 v129, v129, v239
	v_fma_f32 v126, v192, s82, v126
	v_fma_f32 v127, v193, s82, v127
	v_fma_f32 v128, v194, s82, v128
	v_fma_f32 v129, v195, s82, v129
	global_store_dwordx4 v228, v[126:129], s[10:11] offset:0
	v_mul_f32_e32 v122, v122, v240
	v_mul_f32_e32 v123, v123, v241
	v_mul_f32_e32 v124, v124, v242
	v_mul_f32_e32 v125, v125, v243
	v_fma_f32 v122, v196, s82, v122
	v_fma_f32 v123, v197, s82, v123
	v_fma_f32 v124, v198, s82, v124
	v_fma_f32 v125, v199, s82, v125
	global_store_dwordx4 v228, v[122:125], s[10:11] offset:64
	v_mul_f32_e32 v118, v118, v244
	v_mul_f32_e32 v119, v119, v245
	v_mul_f32_e32 v120, v120, v246
	v_mul_f32_e32 v121, v121, v247
	v_fma_f32 v118, v200, s82, v118
	v_fma_f32 v119, v201, s82, v119
	v_fma_f32 v120, v202, s82, v120
	v_fma_f32 v121, v203, s82, v121
	global_store_dwordx4 v228, v[118:121], s[10:11] offset:128
	v_mul_f32_e32 v114, v114, v248
	v_mul_f32_e32 v115, v115, v249
	v_mul_f32_e32 v116, v116, v250
	v_mul_f32_e32 v117, v117, v251
	v_fma_f32 v114, v204, s82, v114
	v_fma_f32 v115, v205, s82, v115
	v_fma_f32 v116, v206, s82, v116
	v_fma_f32 v117, v207, s82, v117
	global_store_dwordx4 v228, v[114:117], s[10:11] offset:192
	v_mul_f32_e32 v110, v110, v236
	v_mul_f32_e32 v111, v111, v237
	v_mul_f32_e32 v112, v112, v238
	v_mul_f32_e32 v113, v113, v239
	v_fma_f32 v110, v208, s82, v110
	v_fma_f32 v111, v209, s82, v111
	v_fma_f32 v112, v210, s82, v112
	v_fma_f32 v113, v211, s82, v113
	global_store_dwordx4 v229, v[110:113], s[10:11] offset:0
	v_mul_f32_e32 v106, v106, v240
	v_mul_f32_e32 v107, v107, v241
	v_mul_f32_e32 v108, v108, v242
	v_mul_f32_e32 v109, v109, v243
	v_fma_f32 v106, v212, s82, v106
	v_fma_f32 v107, v213, s82, v107
	v_fma_f32 v108, v214, s82, v108
	v_fma_f32 v109, v215, s82, v109
	global_store_dwordx4 v229, v[106:109], s[10:11] offset:64
	v_mul_f32_e32 v102, v102, v244
	v_mul_f32_e32 v103, v103, v245
	v_mul_f32_e32 v104, v104, v246
	v_mul_f32_e32 v105, v105, v247
	v_fma_f32 v102, v216, s82, v102
	v_fma_f32 v103, v217, s82, v103
	v_fma_f32 v104, v218, s82, v104
	v_fma_f32 v105, v219, s82, v105
	global_store_dwordx4 v229, v[102:105], s[10:11] offset:128
	v_mul_f32_e32 v98, v98, v248
	v_mul_f32_e32 v99, v99, v249
	v_mul_f32_e32 v100, v100, v250
	v_mul_f32_e32 v101, v101, v251
	v_fma_f32 v98, v220, s82, v98
	v_fma_f32 v99, v221, s82, v99
	v_fma_f32 v100, v222, s82, v100
	v_fma_f32 v101, v223, s82, v101
	global_store_dwordx4 v229, v[98:101], s[10:11] offset:192
	global_load_dwordx4 v[192:195], v232, s[8:9] offset:0
	global_load_dwordx4 v[196:199], v232, s[8:9] offset:64
	global_load_dwordx4 v[200:203], v232, s[8:9] offset:128
	global_load_dwordx4 v[204:207], v232, s[8:9] offset:192
	global_load_dwordx4 v[208:211], v233, s[8:9] offset:0
	global_load_dwordx4 v[212:215], v233, s[8:9] offset:64
	global_load_dwordx4 v[216:219], v233, s[8:9] offset:128
	global_load_dwordx4 v[220:223], v233, s[8:9] offset:192
	s_waitcnt vmcnt(16)
;   DI float* MOD() const { return (float*)(p.ws + WS_MOD); }
;   DI void operator()(int m, int n, f32x4 v) const {
;     ...
;     const float4 xo = (l == 0) ? *(const float4*)((lat ? xin_lat : xin_ctx) + off) : *(const float4*)xp;
;     const float4 g = *(const float4*)(MOD + (l * 3 + mod_row(m)) * 3072 + 2048 + n);
;     *(float4*)xp = make_float4(ALPHA * xo.x + g.x * v[0], ALPHA * xo.y + g.y * v[1], ALPHA * xo.z + g.z * v[2], ALPHA * xo.w + g.w * v[3]);
	v_mul_f32_e32 v94, v94, v236
	v_mul_f32_e32 v95, v95, v237
	v_mul_f32_e32 v96, v96, v238
	v_mul_f32_e32 v97, v97, v239
	v_fma_f32 v94, v132, s82, v94
	v_fma_f32 v95, v133, s82, v95
	v_fma_f32 v96, v134, s82, v96
	v_fma_f32 v97, v135, s82, v97
	global_store_dwordx4 v230, v[94:97], s[10:11] offset:0
	v_mul_f32_e32 v90, v90, v240
	v_mul_f32_e32 v91, v91, v241
	v_mul_f32_e32 v92, v92, v242
	v_mul_f32_e32 v93, v93, v243
	v_fma_f32 v90, v136, s82, v90
	v_fma_f32 v91, v137, s82, v91
	v_fma_f32 v92, v138, s82, v92
	v_fma_f32 v93, v139, s82, v93
	global_store_dwordx4 v230, v[90:93], s[10:11] offset:64
	v_mul_f32_e32 v86, v86, v244
	v_mul_f32_e32 v87, v87, v245
	v_mul_f32_e32 v88, v88, v246
	v_mul_f32_e32 v89, v89, v247
	v_fma_f32 v86, v140, s82, v86
	v_fma_f32 v87, v141, s82, v87
	v_fma_f32 v88, v142, s82, v88
	v_fma_f32 v89, v143, s82, v89
	global_store_dwordx4 v230, v[86:89], s[10:11] offset:128
	v_mul_f32_e32 v82, v82, v248
	v_mul_f32_e32 v83, v83, v249
	v_mul_f32_e32 v84, v84, v250
	v_mul_f32_e32 v85, v85, v251
	v_fma_f32 v82, v144, s82, v82
	v_fma_f32 v83, v145, s82, v83
	v_fma_f32 v84, v146, s82, v84
	v_fma_f32 v85, v147, s82, v85
	global_store_dwordx4 v230, v[82:85], s[10:11] offset:192
	v_mul_f32_e32 v78, v78, v236
	v_mul_f32_e32 v79, v79, v237
	v_mul_f32_e32 v80, v80, v238
	v_mul_f32_e32 v81, v81, v239
	v_fma_f32 v78, v148, s82, v78
	v_fma_f32 v79, v149, s82, v79
	v_fma_f32 v80, v150, s82, v80
	v_fma_f32 v81, v151, s82, v81
	global_store_dwordx4 v231, v[78:81], s[10:11] offset:0
	v_mul_f32_e32 v74, v74, v240
	v_mul_f32_e32 v75, v75, v241
	v_mul_f32_e32 v76, v76, v242
	v_mul_f32_e32 v77, v77, v243
	v_fma_f32 v74, v152, s82, v74
	v_fma_f32 v75, v153, s82, v75
	v_fma_f32 v76, v154, s82, v76
	v_fma_f32 v77, v155, s82, v77
	global_store_dwordx4 v231, v[74:77], s[10:11] offset:64
	v_mul_f32_e32 v70, v70, v244
	v_mul_f32_e32 v71, v71, v245
	v_mul_f32_e32 v72, v72, v246
	v_mul_f32_e32 v73, v73, v247
	v_fma_f32 v70, v164, s82, v70
	v_fma_f32 v71, v165, s82, v71
	v_fma_f32 v72, v166, s82, v72
	v_fma_f32 v73, v167, s82, v73
	global_store_dwordx4 v231, v[70:73], s[10:11] offset:128
	v_mul_f32_e32 v66, v66, v248
	v_mul_f32_e32 v67, v67, v249
	v_mul_f32_e32 v68, v68, v250
	v_mul_f32_e32 v69, v69, v251
	v_fma_f32 v66, v224, s82, v66
	v_fma_f32 v67, v225, s82, v67
	v_fma_f32 v68, v226, s82, v68
	v_fma_f32 v69, v227, s82, v69
	global_store_dwordx4 v231, v[66:69], s[10:11] offset:192
	global_load_dwordx4 v[132:135], v234, s[8:9] offset:0
	global_load_dwordx4 v[136:139], v234, s[8:9] offset:64
	global_load_dwordx4 v[140:143], v234, s[8:9] offset:128
	global_load_dwordx4 v[144:147], v234, s[8:9] offset:192
	global_load_dwordx4 v[148:151], v235, s[8:9] offset:0
	global_load_dwordx4 v[152:155], v235, s[8:9] offset:64
	global_load_dwordx4 v[164:167], v235, s[8:9] offset:128
	global_load_dwordx4 v[224:227], v235, s[8:9] offset:192
	s_waitcnt vmcnt(16)
	v_mul_f32_e32 v62, v62, v236
	v_mul_f32_e32 v63, v63, v237
	v_mul_f32_e32 v64, v64, v238
	v_mul_f32_e32 v65, v65, v239
	v_fma_f32 v62, v192, s82, v62
	v_fma_f32 v63, v193, s82, v63
	v_fma_f32 v64, v194, s82, v64
	v_fma_f32 v65, v195, s82, v65
	global_store_dwordx4 v232, v[62:65], s[10:11] offset:0
	v_mul_f32_e32 v58, v58, v240
	v_mul_f32_e32 v59, v59, v241
	v_mul_f32_e32 v60, v60, v242
	v_mul_f32_e32 v61, v61, v243
	v_fma_f32 v58, v196, s82, v58
	v_fma_f32 v59, v197, s82, v59
	v_fma_f32 v60, v198, s82, v60
	v_fma_f32 v61, v199, s82, v61
	global_store_dwordx4 v232, v[58:61], s[10:11] offset:64
	v_mul_f32_e32 v54, v54, v244
	v_mul_f32_e32 v55, v55, v245
	v_mul_f32_e32 v56, v56, v246
	v_mul_f32_e32 v57, v57, v247
	v_fma_f32 v54, v200, s82, v54
	v_fma_f32 v55, v201, s82, v55
	v_fma_f32 v56, v202, s82, v56
	v_fma_f32 v57, v203, s82, v57
	global_store_dwordx4 v232, v[54:57], s[10:11] offset:128
	v_mul_f32_e32 v50, v50, v248
	v_mul_f32_e32 v51, v51, v249
	v_mul_f32_e32 v52, v52, v250
	v_mul_f32_e32 v53, v53, v251
	v_fma_f32 v50, v204, s82, v50
	v_fma_f32 v51, v205, s82, v51
	v_fma_f32 v52, v206, s82, v52
	v_fma_f32 v53, v207, s82, v53
	global_store_dwordx4 v232, v[50:53], s[10:11] offset:192
	v_mul_f32_e32 v46, v46, v236
	v_mul_f32_e32 v47, v47, v237
	v_mul_f32_e32 v48, v48, v238
	v_mul_f32_e32 v49, v49, v239
	v_fma_f32 v46, v208, s82, v46
	v_fma_f32 v47, v209, s82, v47
	v_fma_f32 v48, v210, s82, v48
	v_fma_f32 v49, v211, s82, v49
	global_store_dwordx4 v233, v[46:49], s[10:11] offset:0
	v_mul_f32_e32 v42, v42, v240
	v_mul_f32_e32 v43, v43, v241
	v_mul_f32_e32 v44, v44, v242
	v_mul_f32_e32 v45, v45, v243
	v_fma_f32 v42, v212, s82, v42
	v_fma_f32 v43, v213, s82, v43
	v_fma_f32 v44, v214, s82, v44
	v_fma_f32 v45, v215, s82, v45
	global_store_dwordx4 v233, v[42:45], s[10:11] offset:64
	v_mul_f32_e32 v38, v38, v244
	v_mul_f32_e32 v39, v39, v245
	v_mul_f32_e32 v40, v40, v246
	v_mul_f32_e32 v41, v41, v247
	v_fma_f32 v38, v216, s82, v38
	v_fma_f32 v39, v217, s82, v39
	v_fma_f32 v40, v218, s82, v40
	v_fma_f32 v41, v219, s82, v41
	global_store_dwordx4 v233, v[38:41], s[10:11] offset:128
	v_mul_f32_e32 v34, v34, v248
	v_mul_f32_e32 v35, v35, v249
	v_mul_f32_e32 v36, v36, v250
	v_mul_f32_e32 v37, v37, v251
	v_fma_f32 v34, v220, s82, v34
	v_fma_f32 v35, v221, s82, v35
	v_fma_f32 v36, v222, s82, v36
	v_fma_f32 v37, v223, s82, v37
	global_store_dwordx4 v233, v[34:37], s[10:11] offset:192
	s_waitcnt vmcnt(8)
;   DI float* MOD() const { return (float*)(p.ws + WS_MOD); }
;   DI bf16* G() const { return (bf16*)(p.ws + WS_G); }
; template <class F>
; DI void xcd_items(int total, const F& f) {
;   const int G = gridDim.x;
;   if ((G & 7) == 0 && (total & 7) == 0) {
;     const int x = blockIdx.x & 7, j = blockIdx.x >> 3, per = total >> 3, gl = G >> 3;
;     for (int q = j; q < per; q += gl) f(x * per + q);
; template <class AP, class BP, class Epi>
; DI void mfma_gemm_big_tile(const AP& aptr, const BP& bptr, int m0, int n0, int K, const Epi& epi, bf16* lds) {
;     ...
;   asm volatile("s_waitcnt vmcnt(0)" ::: "memory");
;   __syncthreads();
;   DI void operator()(int m, int n, f32x4 v) const {
;     ...
;     const float4 xo = (l == 0) ? *(const float4*)((lat ? xin_lat : xin_ctx) + off) : *(const float4*)xp;
;     const float4 g = *(const float4*)(MOD + (l * 3 + mod_row(m)) * 3072 + 2048 + n);
;     *(float4*)xp = make_float4(ALPHA * xo.x + g.x * v[0], ALPHA * xo.y + g.y * v[1], ALPHA * xo.z + g.z * v[2], ALPHA * xo.w + g.w * v[3]);
	v_mul_f32_e32 v30, v30, v236
	v_mul_f32_e32 v31, v31, v237
	v_mul_f32_e32 v32, v32, v238
	v_mul_f32_e32 v33, v33, v239
	v_fma_f32 v30, v132, s82, v30
	v_fma_f32 v31, v133, s82, v31
	v_fma_f32 v32, v134, s82, v32
	v_fma_f32 v33, v135, s82, v33
	global_store_dwordx4 v234, v[30:33], s[10:11] offset:0
	v_mul_f32_e32 v26, v26, v240
	v_mul_f32_e32 v27, v27, v241
	v_mul_f32_e32 v28, v28, v242
	v_mul_f32_e32 v29, v29, v243
	v_fma_f32 v26, v136, s82, v26
	v_fma_f32 v27, v137, s82, v27
	v_fma_f32 v28, v138, s82, v28
	v_fma_f32 v29, v139, s82, v29
	global_store_dwordx4 v234, v[26:29], s[10:11] offset:64
	v_mul_f32_e32 v22, v22, v244
	v_mul_f32_e32 v23, v23, v245
	v_mul_f32_e32 v24, v24, v246
	v_mul_f32_e32 v25, v25, v247
	v_fma_f32 v22, v140, s82, v22
	v_fma_f32 v23, v141, s82, v23
	v_fma_f32 v24, v142, s82, v24
	v_fma_f32 v25, v143, s82, v25
	global_store_dwordx4 v234, v[22:25], s[10:11] offset:128
	v_mul_f32_e32 v18, v18, v248
	v_mul_f32_e32 v19, v19, v249
	v_mul_f32_e32 v20, v20, v250
	v_mul_f32_e32 v21, v21, v251
	v_fma_f32 v18, v144, s82, v18
	v_fma_f32 v19, v145, s82, v19
	v_fma_f32 v20, v146, s82, v20
	v_fma_f32 v21, v147, s82, v21
	global_store_dwordx4 v234, v[18:21], s[10:11] offset:192
	v_mul_f32_e32 v14, v14, v236
	v_mul_f32_e32 v15, v15, v237
	v_mul_f32_e32 v16, v16, v238
	v_mul_f32_e32 v17, v17, v239
	v_fma_f32 v14, v148, s82, v14
	v_fma_f32 v15, v149, s82, v15
	v_fma_f32 v16, v150, s82, v16
	v_fma_f32 v17, v151, s82, v17
	global_store_dwordx4 v235, v[14:17], s[10:11] offset:0
	v_mul_f32_e32 v10, v10, v240
	v_mul_f32_e32 v11, v11, v241
	v_mul_f32_e32 v12, v12, v242
	v_mul_f32_e32 v13, v13, v243
	v_fma_f32 v10, v152, s82, v10
	v_fma_f32 v11, v153, s82, v11
	v_fma_f32 v12, v154, s82, v12
	v_fma_f32 v13, v155, s82, v13
	global_store_dwordx4 v235, v[10:13], s[10:11] offset:64
	v_mul_f32_e32 v6, v6, v244
	v_mul_f32_e32 v7, v7, v245
	v_mul_f32_e32 v8, v8, v246
	v_mul_f32_e32 v9, v9, v247
	v_fma_f32 v6, v164, s82, v6
	v_fma_f32 v7, v165, s82, v7
	v_fma_f32 v8, v166, s82, v8
	v_fma_f32 v9, v167, s82, v9
	global_store_dwordx4 v235, v[6:9], s[10:11] offset:128
	v_mul_f32_e32 v2, v2, v248
	v_mul_f32_e32 v3, v3, v249
	v_mul_f32_e32 v4, v4, v250
	v_mul_f32_e32 v5, v5, v251
	v_fma_f32 v2, v224, s82, v2
	v_fma_f32 v3, v225, s82, v3
	v_fma_f32 v4, v226, s82, v4
	v_fma_f32 v5, v227, s82, v5
	global_store_dwordx4 v235, v[2:5], s[10:11] offset:192
	s_movk_i32 s2, 0xc00
	v_readlane_b32 s0, v253, 39
	v_readlane_b32 s1, v253, 40
	v_readlane_b32 s16, v252, 41
	v_readlane_b32 s17, v252, 42
	v_readlane_b32 s18, v252, 43
	v_readlane_b32 s19, v252, 44
	v_readlane_b32 s20, v252, 45
	v_readlane_b32 s21, v252, 46
	v_readlane_b32 s22, v252, 47
	v_readlane_b32 s23, v252, 48
	v_readlane_b32 s24, v252, 49
	v_readlane_b32 s25, v252, 50
	v_readlane_b32 s26, v252, 51
	v_readlane_b32 s27, v252, 52
	v_readlane_b32 s28, v252, 53
	v_readlane_b32 s29, v252, 54
	v_readlane_b32 s30, v252, 55
	v_readlane_b32 s31, v252, 56
	s_mov_b64 s[8:9], 0x2000
	s_mov_b64 s[10:11], 0x80
	s_add_i32 s13, s13, s41
	s_cmp_gt_i32 s13, 63
	s_waitcnt vmcnt(0)
	s_waitcnt lgkmcnt(0)
	s_barrier
	s_cbranch_scc1 .LBB0_1113

; #define LDSR(dst, addr, off) asm volatile("ds_read_b128 %0, %1 offset:%2" : "=&v"(dst) : "v"(addr), "n"(off))
; #define LDSR(dst, addr, off) asm volatile("ds_read_b128 %0, %1 offset:%2" : "=&v"(dst) : "v"(addr), "n"(off))
; template <int TRANS, class AP, class BP, class Epi>
; DI void mfma_gemm_tile(const AP& aptr, const BP& bptr, int m0, int n0, int K, const Epi& epi, bf16* lds) {
;     ...
;   for (int ks = 0; ks < nk; ++ks) {
;     if (ks + 1 < nk) asm volatile("s_waitcnt vmcnt(8)\n\ts_barrier" ::: "memory");
;     else asm volatile("s_waitcnt vmcnt(0)\n\ts_barrier" ::: "memory");
;     const unsigned sb_ = lbase + (unsigned)((ks & 1) * (2 * 128 * 64) * 2);
;     const unsigned a0 = sb_ + a_row + sw0, a1 = sb_ + a_row + sw1, b0 = sb_ + b_row + sw0, b1 = sb_ + b_row + sw1;
;     bf16x8 af[2][4], bfr[2][4];
;     LDSR(af[0][0], a0, 0); LDSR(af[0][1], a0, 2048); LDSR(af[0][2], a0, 4096); LDSR(af[0][3], a0, 6144);
;     LDSR(bfr[0][0], b0, 0); LDSR(bfr[0][1], b0, 2048); LDSR(bfr[0][2], b0, 4096); LDSR(bfr[0][3], b0, 6144);
;     LDSR(af[1][0], a1, 0); LDSR(af[1][1], a1, 2048); LDSR(af[1][2], a1, 4096); LDSR(af[1][3], a1, 6144);
;     LDSR(bfr[1][0], b1, 0); LDSR(bfr[1][1], b1, 2048); LDSR(bfr[1][2], b1, 4096); LDSR(bfr[1][3], b1, 6144);
;     asm volatile("s_waitcnt lgkmcnt(0)" : "+v"(af[0][0]), "+v"(af[0][1]), "+v"(af[0][2]), "+v"(af[0][3]), "+v"(bfr[0][0]), "+v"(bfr[0][1]), "+v"(bfr[0][2]), "+v"(bfr[0][3]),
;                  "+v"(af[1][0]), "+v"(af[1][1]), "+v"(af[1][2]), "+v"(af[1][3]), "+v"(bfr[1][0]), "+v"(bfr[1][1]), "+v"(bfr[1][2]), "+v"(bfr[1][3]) : : "memory");
;     if (ks + 2 < nk) {
;       asm volatile("s_barrier" ::: "memory");
;       GEMM_STAGE(ks & 1, ks + 2);
;     }
; #pragma unroll
;     for (int kk = 0; kk < 2; ++kk)
; #pragma unroll
;       for (int i = 0; i < 4; ++i)
; #pragma unroll
;         for (int j = 0; j < 4; ++j)
;           acc[i][j] = TRANS ? __builtin_amdgcn_mfma_f32_16x16x32_bf16(af[kk][i], bfr[kk][j], acc[i][j], 0, 0, 0)
;                             : __builtin_amdgcn_mfma_f32_16x16x32_bf16(bfr[kk][j], af[kk][i], acc[i][j], 0, 0, 0);
;   }
.LBB0_1116:
	s_lshl_b32 s16, s15, 1
	s_and_b32 s16, s16, 0x8000
	v_add_u32_e32 v87, s16, v86
	v_or_b32_e32 v88, s16, v85
	v_add_u32_e32 v104, v87, v83
	v_add_u32_e32 v120, v88, v83
	s_waitcnt vmcnt(8)
	s_barrier
	v_add_u32_e32 v87, v87, v84
	v_add_u32_e32 v152, v88, v84
	ds_read_b128 v[88:91], v104 offset:0
	ds_read_b128 v[92:95], v104 offset:0x800
	ds_read_b128 v[96:99], v104 offset:0x1000
	ds_read_b128 v[100:103], v104 offset:0x1800
	ds_read_b128 v[104:107], v120 offset:0
	ds_read_b128 v[108:111], v120 offset:0x800
	ds_read_b128 v[112:115], v120 offset:0x1000
	ds_read_b128 v[116:119], v120 offset:0x1800
	ds_read_b128 v[120:123], v87 offset:0
	ds_read_b128 v[124:127], v87 offset:0x800
	ds_read_b128 v[128:131], v87 offset:0x1000
	ds_read_b128 v[132:135], v87 offset:0x1800
	ds_read_b128 v[136:139], v152 offset:0
	ds_read_b128 v[140:143], v152 offset:0x800
	ds_read_b128 v[144:147], v152 offset:0x1000
	ds_read_b128 v[148:151], v152 offset:0x1800
	s_add_i32 s16, s14, s16
	s_waitcnt lgkmcnt(0)
	s_barrier
	s_mov_b32 m0, s16
	v_mfma_f32_16x16x32_bf16 v[62:65], v[104:107], v[88:91], v[62:65]
	v_mfma_f32_16x16x32_bf16 v[58:61], v[108:111], v[88:91], v[58:61]
	v_mfma_f32_16x16x32_bf16 v[54:57], v[112:115], v[88:91], v[54:57]
	v_mfma_f32_16x16x32_bf16 v[50:53], v[116:119], v[88:91], v[50:53]
	v_lshl_add_u64 v[88:89], v[80:81], 0, s[0:1]
	v_lshl_add_u64 v[90:91], v[78:79], 0, s[0:1]
	global_load_lds_dwordx4 v[88:89], off
	s_add_i32 m0, s16, 0x4000
	v_mfma_f32_16x16x32_bf16 v[46:49], v[104:107], v[92:95], v[46:49]
	global_load_lds_dwordx4 v[90:91], off
	s_add_i32 m0, s16, 0x1000
	v_mfma_f32_16x16x32_bf16 v[42:45], v[108:111], v[92:95], v[42:45]
	v_mfma_f32_16x16x32_bf16 v[38:41], v[112:115], v[92:95], v[38:41]
	v_mfma_f32_16x16x32_bf16 v[34:37], v[116:119], v[92:95], v[34:37]
	v_lshl_add_u64 v[92:93], v[76:77], 0, s[0:1]
	v_lshl_add_u64 v[94:95], v[74:75], 0, s[0:1]
	global_load_lds_dwordx4 v[92:93], off
	s_add_i32 m0, s16, 0x5000
	v_mfma_f32_16x16x32_bf16 v[30:33], v[104:107], v[96:99], v[30:33]
	global_load_lds_dwordx4 v[94:95], off
	s_add_i32 m0, s16, 0x2000
	v_mfma_f32_16x16x32_bf16 v[26:29], v[108:111], v[96:99], v[26:29]
	v_mfma_f32_16x16x32_bf16 v[22:25], v[112:115], v[96:99], v[22:25]
	v_mfma_f32_16x16x32_bf16 v[18:21], v[116:119], v[96:99], v[18:21]
	v_lshl_add_u64 v[96:97], v[72:73], 0, s[0:1]
	v_lshl_add_u64 v[98:99], v[70:71], 0, s[0:1]
	global_load_lds_dwordx4 v[96:97], off
	s_add_i32 m0, s16, 0x6000
	v_mfma_f32_16x16x32_bf16 v[14:17], v[104:107], v[100:103], v[14:17]
	global_load_lds_dwordx4 v[98:99], off
	s_add_i32 m0, s16, 0x3000
	v_mfma_f32_16x16x32_bf16 v[10:13], v[108:111], v[100:103], v[10:13]
	v_mfma_f32_16x16x32_bf16 v[6:9], v[112:115], v[100:103], v[6:9]
	v_mfma_f32_16x16x32_bf16 v[2:5], v[116:119], v[100:103], v[2:5]
	v_lshl_add_u64 v[100:101], v[68:69], 0, s[0:1]
	v_lshl_add_u64 v[102:103], v[66:67], 0, s[0:1]
	global_load_lds_dwordx4 v[100:101], off
	s_add_i32 m0, s16, 0x7000
	v_mfma_f32_16x16x32_bf16 v[62:65], v[136:139], v[120:123], v[62:65]
	global_load_lds_dwordx4 v[102:103], off
	s_add_u32 s0, s0, 0x80
	v_mfma_f32_16x16x32_bf16 v[58:61], v[140:143], v[120:123], v[58:61]
	s_addc_u32 s1, s1, 0
	s_addk_i32 s15, 0x4000
	s_cmpk_eq_i32 s0, 0x700
	v_mfma_f32_16x16x32_bf16 v[54:57], v[144:147], v[120:123], v[54:57]
	v_mfma_f32_16x16x32_bf16 v[50:53], v[148:151], v[120:123], v[50:53]
	v_mfma_f32_16x16x32_bf16 v[46:49], v[136:139], v[124:127], v[46:49]
	v_mfma_f32_16x16x32_bf16 v[42:45], v[140:143], v[124:127], v[42:45]
	v_mfma_f32_16x16x32_bf16 v[38:41], v[144:147], v[124:127], v[38:41]
	v_mfma_f32_16x16x32_bf16 v[34:37], v[148:151], v[124:127], v[34:37]
	v_mfma_f32_16x16x32_bf16 v[30:33], v[136:139], v[128:131], v[30:33]
	v_mfma_f32_16x16x32_bf16 v[26:29], v[140:143], v[128:131], v[26:29]
	v_mfma_f32_16x16x32_bf16 v[22:25], v[144:147], v[128:131], v[22:25]
	v_mfma_f32_16x16x32_bf16 v[18:21], v[148:151], v[128:131], v[18:21]
	v_mfma_f32_16x16x32_bf16 v[14:17], v[136:139], v[132:135], v[14:17]
	v_mfma_f32_16x16x32_bf16 v[10:13], v[140:143], v[132:135], v[10:13]
	v_mfma_f32_16x16x32_bf16 v[6:9], v[144:147], v[132:135], v[6:9]
	v_mfma_f32_16x16x32_bf16 v[2:5], v[148:151], v[132:135], v[2:5]
	s_cbranch_scc0 .LBB0_1116
	v_add_u32_e32 v120, v86, v84
	v_add_u32_e32 v104, v85, v83
	s_waitcnt vmcnt(8)
	s_barrier
	v_add_u32_e32 v87, v86, v83
	v_add_u32_e32 v136, v85, v84
	ds_read_b128 v[66:69], v87 offset:0
	ds_read_b128 v[70:73], v87 offset:0x800
	ds_read_b128 v[74:77], v87 offset:0x1000
	ds_read_b128 v[78:81], v87 offset:0x1800
	ds_read_b128 v[88:91], v104 offset:0
	ds_read_b128 v[92:95], v104 offset:0x800
	ds_read_b128 v[96:99], v104 offset:0x1000
	ds_read_b128 v[100:103], v104 offset:0x1800
	ds_read_b128 v[104:107], v120 offset:0
	ds_read_b128 v[108:111], v120 offset:0x800
	ds_read_b128 v[112:115], v120 offset:0x1000
	ds_read_b128 v[116:119], v120 offset:0x1800
	ds_read_b128 v[120:123], v136 offset:0
	ds_read_b128 v[124:127], v136 offset:0x800
	ds_read_b128 v[128:131], v136 offset:0x1000
	ds_read_b128 v[132:135], v136 offset:0x1800
	s_waitcnt lgkmcnt(0)
	s_waitcnt vmcnt(0)
	s_barrier
; template <int TRANS, class AP, class BP, class Epi>
; DI void mfma_gemm_tile(const AP& aptr, const BP& bptr, int m0, int n0, int K, const Epi& epi, bf16* lds) {
;     ...
; #pragma unroll
;     for (int kk = 0; kk < 2; ++kk)
; #pragma unroll
;       for (int i = 0; i < 4; ++i)
; #pragma unroll
;         for (int j = 0; j < 4; ++j)
;           acc[i][j] = TRANS ? __builtin_amdgcn_mfma_f32_16x16x32_bf16(af[kk][i], bfr[kk][j], acc[i][j], 0, 0, 0)
;                             : __builtin_amdgcn_mfma_f32_16x16x32_bf16(bfr[kk][j], af[kk][i], acc[i][j], 0, 0, 0);
;   }
;     ...
; #pragma unroll
;   for (int i = 0; i < 4; ++i)
; #pragma unroll
;     for (int j = 0; j < 4; ++j) {
;       if (TRANS) epi(m0 + wm + 16 * i + 4 * lq, n0 + wn + 16 * j + l16, acc[i][j]);
;       else epi(m0 + wm + 16 * i + l16, n0 + wn + 16 * j + 4 * lq, acc[i][j]);
;     }
	s_movk_i32 s10, 0xc00
	v_mfma_f32_16x16x32_bf16 v[62:65], v[88:91], v[66:69], v[62:65]
	v_readlane_b32 s2, v253, 39
	v_readlane_b32 s3, v253, 40
	s_add_i32 s9, s9, s40
	v_mfma_f32_16x16x32_bf16 v[14:17], v[88:91], v[78:81], v[14:17]
	s_add_i32 s8, s8, s73
	s_add_i32 s7, s7, s67
	s_cmp_gt_i32 s9, 31
	v_mfma_f32_16x16x32_bf16 v[10:13], v[92:95], v[78:81], v[10:13]
	v_mfma_f32_16x16x32_bf16 v[6:9], v[96:99], v[78:81], v[6:9]
	v_mfma_f32_16x16x32_bf16 v[2:5], v[100:103], v[78:81], v[2:5]
	v_mfma_f32_16x16x32_bf16 v[58:61], v[92:95], v[66:69], v[58:61]
	v_mfma_f32_16x16x32_bf16 v[54:57], v[96:99], v[66:69], v[54:57]
	v_mfma_f32_16x16x32_bf16 v[50:53], v[100:103], v[66:69], v[50:53]
	v_add_u32_e32 v66, 0x8000, v86
	v_add_u32_e32 v86, v66, v83
	v_mfma_f32_16x16x32_bf16 v[46:49], v[88:91], v[70:73], v[46:49]
	v_mfma_f32_16x16x32_bf16 v[42:45], v[92:95], v[70:73], v[42:45]
	v_mfma_f32_16x16x32_bf16 v[38:41], v[96:99], v[70:73], v[38:41]
	v_mfma_f32_16x16x32_bf16 v[34:37], v[100:103], v[70:73], v[34:37]
	v_mfma_f32_16x16x32_bf16 v[30:33], v[88:91], v[74:77], v[30:33]
	v_mfma_f32_16x16x32_bf16 v[26:29], v[92:95], v[74:77], v[26:29]
	v_mfma_f32_16x16x32_bf16 v[22:25], v[96:99], v[74:77], v[22:25]
	v_mfma_f32_16x16x32_bf16 v[18:21], v[100:103], v[74:77], v[18:21]
	v_mfma_f32_16x16x32_bf16 v[62:65], v[120:123], v[104:107], v[62:65]
	v_mfma_f32_16x16x32_bf16 v[14:17], v[120:123], v[116:119], v[14:17]
	v_mfma_f32_16x16x32_bf16 v[10:13], v[124:127], v[116:119], v[10:13]
	v_mfma_f32_16x16x32_bf16 v[6:9], v[128:131], v[116:119], v[6:9]
	v_mfma_f32_16x16x32_bf16 v[2:5], v[132:135], v[116:119], v[2:5]
	v_add_u32_e32 v116, v66, v84
	v_or_b32_e32 v66, 0x8000, v85
	v_add_u32_e32 v83, v66, v83
	v_mfma_f32_16x16x32_bf16 v[58:61], v[124:127], v[104:107], v[58:61]
	v_mfma_f32_16x16x32_bf16 v[54:57], v[128:131], v[104:107], v[54:57]
	v_mfma_f32_16x16x32_bf16 v[50:53], v[132:135], v[104:107], v[50:53]
	v_mfma_f32_16x16x32_bf16 v[46:49], v[120:123], v[108:111], v[46:49]
	v_mfma_f32_16x16x32_bf16 v[42:45], v[124:127], v[108:111], v[42:45]
	v_mfma_f32_16x16x32_bf16 v[38:41], v[128:131], v[108:111], v[38:41]
	v_mfma_f32_16x16x32_bf16 v[34:37], v[132:135], v[108:111], v[34:37]
	v_mfma_f32_16x16x32_bf16 v[30:33], v[120:123], v[112:115], v[30:33]
	v_mfma_f32_16x16x32_bf16 v[26:29], v[124:127], v[112:115], v[26:29]
	v_mfma_f32_16x16x32_bf16 v[22:25], v[128:131], v[112:115], v[22:25]
	v_mfma_f32_16x16x32_bf16 v[18:21], v[132:135], v[112:115], v[18:21]
	v_add_u32_e32 v132, v66, v84
	ds_read_b128 v[66:69], v86 offset:0
	ds_read_b128 v[70:73], v86 offset:0x800
	ds_read_b128 v[74:77], v86 offset:0x1000
	ds_read_b128 v[78:81], v86 offset:0x1800
	ds_read_b128 v[84:87], v83 offset:0
	ds_read_b128 v[88:91], v83 offset:0x800
	ds_read_b128 v[92:95], v83 offset:0x1000
	ds_read_b128 v[96:99], v83 offset:0x1800
	ds_read_b128 v[100:103], v116 offset:0
	ds_read_b128 v[104:107], v116 offset:0x800
	ds_read_b128 v[108:111], v116 offset:0x1000
	ds_read_b128 v[112:115], v116 offset:0x1800
	ds_read_b128 v[116:119], v132 offset:0
	ds_read_b128 v[120:123], v132 offset:0x800
	ds_read_b128 v[124:127], v132 offset:0x1000
	ds_read_b128 v[128:131], v132 offset:0x1800
	s_nop 0
	s_waitcnt lgkmcnt(0)
	s_nop 0
	v_mfma_f32_16x16x32_bf16 v[62:65], v[84:87], v[66:69], v[62:65]
	v_mfma_f32_16x16x32_bf16 v[14:17], v[84:87], v[78:81], v[14:17]
	v_mfma_f32_16x16x32_bf16 v[10:13], v[88:91], v[78:81], v[10:13]
	v_mfma_f32_16x16x32_bf16 v[6:9], v[92:95], v[78:81], v[6:9]
	v_mfma_f32_16x16x32_bf16 v[2:5], v[96:99], v[78:81], v[2:5]
	v_readlane_b32 s12, v252, 0
	v_readlane_b32 s13, v252, 1
	v_readlane_b32 s14, v252, 2
	v_readlane_b32 s15, v252, 3
	v_mfma_f32_16x16x32_bf16 v[46:49], v[84:87], v[70:73], v[46:49]
	v_mfma_f32_16x16x32_bf16 v[42:45], v[88:91], v[70:73], v[42:45]
	v_mfma_f32_16x16x32_bf16 v[38:41], v[92:95], v[70:73], v[38:41]
	v_mfma_f32_16x16x32_bf16 v[34:37], v[96:99], v[70:73], v[34:37]
	v_readlane_b32 s12, v252, 41
	v_mfma_f32_16x16x32_bf16 v[30:33], v[84:87], v[74:77], v[30:33]
	v_readlane_b32 s13, v252, 42
	v_readlane_b32 s16, v252, 45
	v_readlane_b32 s17, v252, 46
	v_mfma_f32_16x16x32_bf16 v[84:87], v[116:119], v[100:103], v[62:65]
	v_readlane_b32 s14, v252, 43
	v_mfma_f32_16x16x32_bf16 v[26:29], v[88:91], v[74:77], v[26:29]
	v_mfma_f32_16x16x32_bf16 v[22:25], v[92:95], v[74:77], v[22:25]
	v_readlane_b32 s15, v252, 44
	v_readlane_b32 s18, v252, 47
	v_mfma_f32_16x16x32_bf16 v[18:21], v[96:99], v[74:77], v[18:21]
	v_mfma_f32_16x16x32_bf16 v[58:61], v[88:91], v[66:69], v[58:61]
	s_mov_b64 s[12:13], 0x2000
	s_mov_b64 s[16:17], 0x80
	v_readlane_b32 s19, v252, 48
	v_mfma_f32_16x16x32_bf16 v[54:57], v[92:95], v[66:69], v[54:57]
	v_readlane_b32 s20, v252, 49
	v_readlane_b32 s21, v252, 50
	v_readlane_b32 s22, v252, 51
	v_mfma_f32_16x16x32_bf16 v[50:53], v[96:99], v[66:69], v[50:53]
	v_mfma_f32_16x16x32_bf16 v[58:61], v[120:123], v[100:103], v[58:61]
	v_readlane_b32 s23, v252, 52
	v_readlane_b32 s24, v252, 53
	v_readlane_b32 s25, v252, 54
	v_mfma_f32_16x16x32_bf16 v[54:57], v[124:127], v[100:103], v[54:57]
	v_readlane_b32 s26, v252, 55
	v_readlane_b32 s27, v252, 56
	s_waitcnt vmcnt(0)
	s_nop 0
	v_mfma_f32_16x16x32_bf16 v[50:53], v[128:131], v[100:103], v[50:53]
	v_mfma_f32_16x16x32_bf16 v[46:49], v[116:119], v[104:107], v[46:49]
	s_nop 0
	v_mfma_f32_16x16x32_bf16 v[42:45], v[120:123], v[104:107], v[42:45]
	s_waitcnt vmcnt(0)
	v_mfma_f32_16x16x32_bf16 v[38:41], v[124:127], v[104:107], v[38:41]
	s_waitcnt vmcnt(0)
	v_mfma_f32_16x16x32_bf16 v[34:37], v[128:131], v[104:107], v[34:37]
	s_nop 0
	s_nop 0
	v_mfma_f32_16x16x32_bf16 v[30:33], v[116:119], v[108:111], v[30:33]
	s_waitcnt vmcnt(0)
;   DI float* MOD() const { return (float*)(p.ws + WS_MOD); }
; template <int TRANS, class AP, class BP, class Epi>
; DI void mfma_gemm_tile(const AP& aptr, const BP& bptr, int m0, int n0, int K, const Epi& epi, bf16* lds) {
;     ...
; #pragma unroll
;   for (int i = 0; i < 4; ++i)
; #pragma unroll
;     for (int j = 0; j < 4; ++j) {
;       if (TRANS) epi(m0 + wm + 16 * i + 4 * lq, n0 + wn + 16 * j + l16, acc[i][j]);
;       else epi(m0 + wm + 16 * i + l16, n0 + wn + 16 * j + 4 * lq, acc[i][j]);
;     }
;   DI void operator()(int m, int n, f32x4 v) const {
;     const bool lat = m < MLAT;
;     const size_t off = lat ? (size_t)m * D + n : (size_t)(m - MLAT) * D + n;
;     float* xp = (lat ? x_lat : x_ctx) + off;
;     const float4 xo = (l == 0) ? *(const float4*)((lat ? xin_lat : xin_ctx) + off) : *(const float4*)xp;
;     const float4 g = *(const float4*)(MOD + (l * 3 + mod_row(m)) * 3072 + 2048 + n);
;     *(float4*)xp = make_float4(ALPHA * xo.x + g.x * v[0], ALPHA * xo.y + g.y * v[1], ALPHA * xo.z + g.z * v[2], ALPHA * xo.w + g.w * v[3]);
	v_mfma_f32_16x16x32_bf16 v[26:29], v[120:123], v[108:111], v[26:29]
	s_nop 0
	s_nop 0
	v_mfma_f32_16x16x32_bf16 v[22:25], v[124:127], v[108:111], v[22:25]
	s_waitcnt vmcnt(0)
	v_mfma_f32_16x16x32_bf16 v[18:21], v[128:131], v[108:111], v[18:21]
	s_nop 0
	v_mfma_f32_16x16x32_bf16 v[14:17], v[116:119], v[112:115], v[14:17]
	s_waitcnt vmcnt(0)
	v_mfma_f32_16x16x32_bf16 v[10:13], v[120:123], v[112:115], v[10:13]
	s_nop 0
	s_nop 0
	v_mfma_f32_16x16x32_bf16 v[6:9], v[124:127], v[112:115], v[6:9]
	s_waitcnt vmcnt(0)
	v_mfma_f32_16x16x32_bf16 v[2:5], v[128:131], v[112:115], v[2:5]
	s_waitcnt vmcnt(0)
	s_nop 1
	s_nop 0
	s_waitcnt vmcnt(0)
	s_waitcnt vmcnt(0)
	s_nop 1
	s_nop 0
	s_waitcnt vmcnt(0)
	s_waitcnt vmcnt(0)
	s_nop 1
	s_nop 0
	s_waitcnt vmcnt(0)
	s_nop 1
	s_nop 0
	s_waitcnt vmcnt(0)
	s_waitcnt vmcnt(0)
	s_nop 1
	s_nop 0
	s_waitcnt vmcnt(0)
	s_waitcnt vmcnt(0)
	s_nop 1
	s_nop 0
	s_waitcnt vmcnt(0)
	s_waitcnt vmcnt(0)
	s_nop 1
	s_nop 0
	s_waitcnt vmcnt(0)
	s_nop 1
	s_nop 0
	s_waitcnt vmcnt(0)
	s_waitcnt vmcnt(0)
	s_nop 1
	s_nop 0
	s_waitcnt vmcnt(0)
	s_waitcnt vmcnt(0)
	s_nop 1
	s_nop 0
	s_sub_i32 s2, s9, s40
	s_lshr_b32 s3, s2, 3
	s_lshl_b32 s3, s3, 7
	s_and_b32 s2, s2, 7
	s_lshl_b32 s2, s2, 7
	v_and_b32_e32 v131, 15, v172
	v_bfe_u32 v130, v172, 4, 2
	v_bfe_u32 v132, v172, 7, 1
	v_bfe_u32 v133, v172, 6, 1
	v_lshl_add_u32 v131, v132, 6, v131
	v_lshlrev_b32_e32 v130, 2, v130
	v_lshl_add_u32 v130, v133, 6, v130
	v_add_u32_e32 v131, s3, v131
	v_add_u32_e32 v130, s2, v130
	v_lshlrev_b32_e32 v131, 12, v131
	v_lshlrev_b32_e32 v130, 2, v130
	v_add_u32_e32 v152, v131, v130
	v_add_u32_e32 v153, 0x10000, v152
	v_add_u32_e32 v154, 0x20000, v152
	v_add_u32_e32 v155, 0x30000, v152
	s_add_u32 s12, s88, 0x28000
	s_addc_u32 s13, s89, 0
	v_readlane_b32 s14, v252, 45
	v_readlane_b32 s15, v252, 46
	s_cmp_eq_u32 s86, 0
	s_cselect_b32 s14, s14, s12
	s_cselect_b32 s15, s15, s13
	s_mul_i32 s2, s86, 3
	s_add_i32 s2, s2, 2
	s_mul_i32 s2, s2, 0x3000
	s_add_u32 s2, s2, 0x6000
	s_add_u32 s2, s88, s2
	s_addc_u32 s3, s89, 0
	global_load_dwordx4 v[136:139], v130, s[2:3] offset:0
	global_load_dwordx4 v[140:143], v130, s[2:3] offset:64
	global_load_dwordx4 v[144:147], v130, s[2:3] offset:128
	global_load_dwordx4 v[148:151], v130, s[2:3] offset:192
	global_load_dwordx4 v[192:195], v152, s[14:15] offset:0
	global_load_dwordx4 v[196:199], v152, s[14:15] offset:64
	global_load_dwordx4 v[200:203], v152, s[14:15] offset:128
	global_load_dwordx4 v[204:207], v152, s[14:15] offset:192
	global_load_dwordx4 v[208:211], v153, s[14:15] offset:0
	global_load_dwordx4 v[212:215], v153, s[14:15] offset:64
	global_load_dwordx4 v[216:219], v153, s[14:15] offset:128
	global_load_dwordx4 v[220:223], v153, s[14:15] offset:192
	global_load_dwordx4 v[224:227], v154, s[14:15] offset:0
	global_load_dwordx4 v[228:231], v154, s[14:15] offset:64
	global_load_dwordx4 v[232:235], v154, s[14:15] offset:128
	global_load_dwordx4 v[236:239], v154, s[14:15] offset:192
	global_load_dwordx4 v[240:243], v155, s[14:15] offset:0
	global_load_dwordx4 v[244:247], v155, s[14:15] offset:64
	global_load_dwordx4 v[248:251], v155, s[14:15] offset:128
	global_load_dwordx4 v[164:167], v155, s[14:15] offset:192
	s_waitcnt vmcnt(0)
;   DI float* MOD() const { return (float*)(p.ws + WS_MOD); }
;   DI float* XC() const { return (float*)(p.ws + WS_XC); }
;   DI bf16* WL() const { return (bf16*)(p.ws + WS_WL); }
;   DI bf16* HY() const { return (bf16*)(p.ws + WS_HY); }
;   DI void operator()(int m, int n, f32x4 v) const {
;     ...
;     const float4 xo = (l == 0) ? *(const float4*)((lat ? xin_lat : xin_ctx) + off) : *(const float4*)xp;
;     const float4 g = *(const float4*)(MOD + (l * 3 + mod_row(m)) * 3072 + 2048 + n);
;     *(float4*)xp = make_float4(ALPHA * xo.x + g.x * v[0], ALPHA * xo.y + g.y * v[1], ALPHA * xo.z + g.z * v[2], ALPHA * xo.w + g.w * v[3]);
; __global__ void __launch_bounds__(NT, 2) fwd_kernel(Params p) {
;     ...
;       for (int t = blockIdx.x; t < 32; t += gridDim.x)
;         mfma_gemm_tile<0>(RowPtr{c.HY(), D}, RowPtr{c.WL() + WL_OUT / 2, D}, MLAT + (t >> 3) * 128, (t & 7) * 128, D, EpiResid4{p.x, p.ctx, p.out, c.XC(), c.MOD(), l}, lds);
	v_mul_f32_e32 v62, v62, v136
	v_mul_f32_e32 v63, v63, v137
	v_mul_f32_e32 v64, v64, v138
	v_mul_f32_e32 v65, v65, v139
	v_fma_f32 v62, v192, s82, v62
	v_fma_f32 v63, v193, s82, v63
	v_fma_f32 v64, v194, s82, v64
	v_fma_f32 v65, v195, s82, v65
	global_store_dwordx4 v152, v[62:65], s[12:13] offset:0
	v_mul_f32_e32 v58, v58, v140
	v_mul_f32_e32 v59, v59, v141
	v_mul_f32_e32 v60, v60, v142
	v_mul_f32_e32 v61, v61, v143
	v_fma_f32 v58, v196, s82, v58
	v_fma_f32 v59, v197, s82, v59
	v_fma_f32 v60, v198, s82, v60
	v_fma_f32 v61, v199, s82, v61
	global_store_dwordx4 v152, v[58:61], s[12:13] offset:64
	v_mul_f32_e32 v54, v54, v144
	v_mul_f32_e32 v55, v55, v145
	v_mul_f32_e32 v56, v56, v146
	v_mul_f32_e32 v57, v57, v147
	v_fma_f32 v54, v200, s82, v54
	v_fma_f32 v55, v201, s82, v55
	v_fma_f32 v56, v202, s82, v56
	v_fma_f32 v57, v203, s82, v57
	global_store_dwordx4 v152, v[54:57], s[12:13] offset:128
	v_mul_f32_e32 v50, v50, v148
	v_mul_f32_e32 v51, v51, v149
	v_mul_f32_e32 v52, v52, v150
	v_mul_f32_e32 v53, v53, v151
	v_fma_f32 v50, v204, s82, v50
	v_fma_f32 v51, v205, s82, v51
	v_fma_f32 v52, v206, s82, v52
	v_fma_f32 v53, v207, s82, v53
	global_store_dwordx4 v152, v[50:53], s[12:13] offset:192
	v_mul_f32_e32 v46, v46, v136
	v_mul_f32_e32 v47, v47, v137
	v_mul_f32_e32 v48, v48, v138
	v_mul_f32_e32 v49, v49, v139
	v_fma_f32 v46, v208, s82, v46
	v_fma_f32 v47, v209, s82, v47
	v_fma_f32 v48, v210, s82, v48
	v_fma_f32 v49, v211, s82, v49
	global_store_dwordx4 v153, v[46:49], s[12:13] offset:0
	v_mul_f32_e32 v42, v42, v140
	v_mul_f32_e32 v43, v43, v141
	v_mul_f32_e32 v44, v44, v142
	v_mul_f32_e32 v45, v45, v143
	v_fma_f32 v42, v212, s82, v42
	v_fma_f32 v43, v213, s82, v43
	v_fma_f32 v44, v214, s82, v44
	v_fma_f32 v45, v215, s82, v45
	global_store_dwordx4 v153, v[42:45], s[12:13] offset:64
	v_mul_f32_e32 v38, v38, v144
	v_mul_f32_e32 v39, v39, v145
	v_mul_f32_e32 v40, v40, v146
	v_mul_f32_e32 v41, v41, v147
	v_fma_f32 v38, v216, s82, v38
	v_fma_f32 v39, v217, s82, v39
	v_fma_f32 v40, v218, s82, v40
	v_fma_f32 v41, v219, s82, v41
	global_store_dwordx4 v153, v[38:41], s[12:13] offset:128
	v_mul_f32_e32 v34, v34, v148
	v_mul_f32_e32 v35, v35, v149
	v_mul_f32_e32 v36, v36, v150
	v_mul_f32_e32 v37, v37, v151
	v_fma_f32 v34, v220, s82, v34
	v_fma_f32 v35, v221, s82, v35
	v_fma_f32 v36, v222, s82, v36
	v_fma_f32 v37, v223, s82, v37
	global_store_dwordx4 v153, v[34:37], s[12:13] offset:192
	v_mul_f32_e32 v30, v30, v136
	v_mul_f32_e32 v31, v31, v137
	v_mul_f32_e32 v32, v32, v138
	v_mul_f32_e32 v33, v33, v139
	v_fma_f32 v30, v224, s82, v30
	v_fma_f32 v31, v225, s82, v31
	v_fma_f32 v32, v226, s82, v32
	v_fma_f32 v33, v227, s82, v33
	global_store_dwordx4 v154, v[30:33], s[12:13] offset:0
	v_mul_f32_e32 v26, v26, v140
	v_mul_f32_e32 v27, v27, v141
	v_mul_f32_e32 v28, v28, v142
	v_mul_f32_e32 v29, v29, v143
	v_fma_f32 v26, v228, s82, v26
	v_fma_f32 v27, v229, s82, v27
	v_fma_f32 v28, v230, s82, v28
	v_fma_f32 v29, v231, s82, v29
	global_store_dwordx4 v154, v[26:29], s[12:13] offset:64
	v_mul_f32_e32 v22, v22, v144
	v_mul_f32_e32 v23, v23, v145
	v_mul_f32_e32 v24, v24, v146
	v_mul_f32_e32 v25, v25, v147
	v_fma_f32 v22, v232, s82, v22
	v_fma_f32 v23, v233, s82, v23
	v_fma_f32 v24, v234, s82, v24
	v_fma_f32 v25, v235, s82, v25
	global_store_dwordx4 v154, v[22:25], s[12:13] offset:128
	v_mul_f32_e32 v18, v18, v148
	v_mul_f32_e32 v19, v19, v149
	v_mul_f32_e32 v20, v20, v150
	v_mul_f32_e32 v21, v21, v151
	v_fma_f32 v18, v236, s82, v18
	v_fma_f32 v19, v237, s82, v19
	v_fma_f32 v20, v238, s82, v20
	v_fma_f32 v21, v239, s82, v21
	global_store_dwordx4 v154, v[18:21], s[12:13] offset:192
	v_mul_f32_e32 v14, v14, v136
	v_mul_f32_e32 v15, v15, v137
	v_mul_f32_e32 v16, v16, v138
	v_mul_f32_e32 v17, v17, v139
	v_fma_f32 v14, v240, s82, v14
	v_fma_f32 v15, v241, s82, v15
	v_fma_f32 v16, v242, s82, v16
	v_fma_f32 v17, v243, s82, v17
	global_store_dwordx4 v155, v[14:17], s[12:13] offset:0
	v_mul_f32_e32 v10, v10, v140
	v_mul_f32_e32 v11, v11, v141
	v_mul_f32_e32 v12, v12, v142
	v_mul_f32_e32 v13, v13, v143
	v_fma_f32 v10, v244, s82, v10
	v_fma_f32 v11, v245, s82, v11
	v_fma_f32 v12, v246, s82, v12
	v_fma_f32 v13, v247, s82, v13
	global_store_dwordx4 v155, v[10:13], s[12:13] offset:64
	v_mul_f32_e32 v6, v6, v144
	v_mul_f32_e32 v7, v7, v145
	v_mul_f32_e32 v8, v8, v146
	v_mul_f32_e32 v9, v9, v147
	v_fma_f32 v6, v248, s82, v6
	v_fma_f32 v7, v249, s82, v7
	v_fma_f32 v8, v250, s82, v8
	v_fma_f32 v9, v251, s82, v9
	global_store_dwordx4 v155, v[6:9], s[12:13] offset:128
	v_mul_f32_e32 v2, v2, v148
	v_mul_f32_e32 v3, v3, v149
	v_mul_f32_e32 v4, v4, v150
	v_mul_f32_e32 v5, v5, v151
	v_fma_f32 v2, v164, s82, v2
	v_fma_f32 v3, v165, s82, v3
	v_fma_f32 v4, v166, s82, v4
	v_fma_f32 v5, v167, s82, v5
	global_store_dwordx4 v155, v[2:5], s[12:13] offset:192
	v_readlane_b32 s2, v253, 39
	v_readlane_b32 s3, v253, 40
	v_readlane_b32 s14, v252, 43
	v_readlane_b32 s15, v252, 44
	s_mov_b64 s[12:13], 0x2000
	s_cmp_gt_i32 s9, 31
	s_waitcnt vmcnt(0)
	s_waitcnt lgkmcnt(0)
	s_barrier
	s_cbranch_scc0 .LBB0_1115

; DI int otid() { int t = threadIdx.x; asm volatile("" : "+v"(t)); return t; }
;   DI float* xrow(int row) const { return row < MLAT ? p.out + (size_t)row * D : XC() + (size_t)(row - MLAT) * D; }
; DI void ln_row(const Ctx& c, int row, int l_post, int l_next, int lane) {
;   const Params& p = c.p;
;     const bool lat = row < MLAT;
;     const bool do_post = (l_post >= 0) && (lat || l_post <= 1);
;     const bool do_h = (l_next >= 0) && (lat || l_next <= 2);
;     if (!do_post && !do_h) return;
;     if (l_post >= 0 && !do_post) return;
;     const float* src = (l_post < 0) ? c.xin(row) : c.xrow(row);
;     float v[16];
; #pragma unroll
;     for (int i = 0; i < 4; ++i) { const float4 t = *(const float4*)(src + i * 256 + lane * 4); v[i * 4] = t.x; v[i * 4 + 1] = t.y; v[i * 4 + 2] = t.z; v[i * 4 + 3] = t.w; }
;     ...
;       const float rstd = rsqrtf(wave_sum(q) * (1.f / D) + LN_EPS);
; DI void phase_ln(const Ctx& c, int l_post, int l_next) {
;   const int tid = otid(), lane = tid & 63;
;   const int wv = (blockIdx.x * NT + tid) >> 6, nw = (gridDim.x * NT) >> 6;
;   for (int row = wv; row < MT; row += 2 * nw) { ln_row(c, row, l_post, l_next, lane); if (row + nw < MT) ln_row(c, row + nw, l_post, l_next, lane); }
; }
.Llnl_entry:
	v_readlane_b32 s0, v252, 32
	v_lshrrev_b32_e32 v2, 6, v172
	s_nop 0
	v_readfirstlane_b32 s1, v2
	s_lshr_b32 s0, s0, 6
	s_add_i32 s10, s0, s1
	v_mbcnt_lo_u32_b32 v2, -1, 0
	v_mbcnt_hi_u32_b32 v2, -1, v2
	v_xor_b32_e32 v5, 16, v2
	v_lshlrev_b32_e32 v5, 2, v5
	v_lshlrev_b32_e32 v14, 3, v2
	v_lshlrev_b32_e32 v2, 4, v2
	s_cmp_lt_u32 s10, 0x4000
	s_cbranch_scc1 .Llnl_go
	s_cmp_lt_u32 s86, 2
	s_cbranch_scc0 .Llnl_exit
.Llnl_go:
	v_readlane_b32 s30, v252, 2
	v_readlane_b32 s31, v252, 3
	v_readlane_b32 s2, v252, 53
	v_readlane_b32 s3, v252, 54
	v_readlane_b32 s24, v252, 55
	v_readlane_b32 s25, v252, 56
	s_lshl_b32 s20, s86, 12
	s_add_u32 s2, s2, s20
	s_addc_u32 s3, s3, 0
	s_add_u32 s24, s24, s20
	s_addc_u32 s25, s25, 0
	global_load_dwordx4 v[20:23], v2, s[2:3] offset:0
	global_load_dwordx4 v[24:27], v2, s[2:3] offset:1024
	global_load_dwordx4 v[28:31], v2, s[2:3] offset:2048
	global_load_dwordx4 v[32:35], v2, s[2:3] offset:3072
	global_load_dwordx4 v[36:39], v2, s[24:25] offset:0
	global_load_dwordx4 v[40:43], v2, s[24:25] offset:1024
	global_load_dwordx4 v[44:47], v2, s[24:25] offset:2048
	global_load_dwordx4 v[48:51], v2, s[24:25] offset:3072
	s_add_u32 s20, s86, 1
	s_mul_i32 s20, s20, 3
	s_cmp_lt_u32 s10, 0x4000
	s_cbranch_scc0 .Llnl_c0
	s_lshl_b32 s2, s10, 12
	s_add_u32 s2, s30, s2
	s_addc_u32 s3, s31, 0
	s_lshr_b32 s14, s10, 13
	s_branch .Llnl_j0
.Llnl_c0:
	s_sub_u32 s2, s10, 0x4000
	s_lshl_b32 s2, s2, 12
	s_add_u32 s2, s88, s2
	s_addc_u32 s3, s89, 0
	s_add_u32 s2, s2, 0x28000
	s_addc_u32 s3, s3, 0
	s_mov_b32 s14, 2
.Llnl_j0:
	global_load_dwordx4 v[52:55], v2, s[2:3] offset:0
	global_load_dwordx4 v[56:59], v2, s[2:3] offset:1024
	global_load_dwordx4 v[60:63], v2, s[2:3] offset:2048
	global_load_dwordx4 v[64:67], v2, s[2:3] offset:3072
	s_add_u32 s14, s14, s20
	s_mul_i32 s14, s14, 0x3000
	s_add_u32 s24, s88, s14
	s_addc_u32 s25, s89, 0
	s_add_u32 s24, s24, 0x4000
	s_addc_u32 s25, s25, 0
	global_load_dwordx4 v[84:87], v2, s[24:25] offset:0
	global_load_dwordx4 v[88:91], v2, s[24:25] offset:1024
	global_load_dwordx4 v[92:95], v2, s[24:25] offset:2048
	global_load_dwordx4 v[96:99], v2, s[24:25] offset:3072
	s_add_u32 s24, s24, 0x1000
	s_addc_u32 s25, s25, 0
	global_load_dwordx4 v[100:103], v2, s[24:25] offset:0
	global_load_dwordx4 v[104:107], v2, s[24:25] offset:1024
	global_load_dwordx4 v[108:111], v2, s[24:25] offset:2048
	global_load_dwordx4 v[112:115], v2, s[24:25] offset:3072
.Llnl_loop:
	s_add_u32 s12, s10, 0x800
	s_cmp_lt_u32 s12, 0x4200
	s_cbranch_scc0 .Llnl_lastA
	s_cmp_lt_u32 s12, 0x4000
	s_cbranch_scc1 .Llnl_preA
	s_cmp_lt_u32 s86, 2
	s_cbranch_scc0 .Llnl_lastA
.Llnl_preA:
	s_cmp_lt_u32 s12, 0x4000
	s_cbranch_scc0 .Llnl_c1
	s_lshl_b32 s2, s12, 12
	s_add_u32 s2, s30, s2
	s_addc_u32 s3, s31, 0
	s_lshr_b32 s14, s12, 13
	s_branch .Llnl_j1
.Llnl_c1:
	s_sub_u32 s2, s12, 0x4000
	s_lshl_b32 s2, s2, 12
	s_add_u32 s2, s88, s2
	s_addc_u32 s3, s89, 0
	s_add_u32 s2, s2, 0x28000
	s_addc_u32 s3, s3, 0
	s_mov_b32 s14, 2
.Llnl_j1:
	global_load_dwordx4 v[68:71], v2, s[2:3] offset:0
	global_load_dwordx4 v[72:75], v2, s[2:3] offset:1024
	global_load_dwordx4 v[76:79], v2, s[2:3] offset:2048
	global_load_dwordx4 v[80:83], v2, s[2:3] offset:3072
	s_add_u32 s14, s14, s20
	s_mul_i32 s14, s14, 0x3000
	s_add_u32 s24, s88, s14
	s_addc_u32 s25, s89, 0
	s_add_u32 s24, s24, 0x4000
	s_addc_u32 s25, s25, 0
	global_load_dwordx4 v[116:119], v2, s[24:25] offset:0
	global_load_dwordx4 v[120:123], v2, s[24:25] offset:1024
	global_load_dwordx4 v[124:127], v2, s[24:25] offset:2048
	global_load_dwordx4 v[128:131], v2, s[24:25] offset:3072
	s_add_u32 s24, s24, 0x1000
	s_addc_u32 s25, s25, 0
	global_load_dwordx4 v[132:135], v2, s[24:25] offset:0
	global_load_dwordx4 v[136:139], v2, s[24:25] offset:1024
	global_load_dwordx4 v[140:143], v2, s[24:25] offset:2048
	global_load_dwordx4 v[144:147], v2, s[24:25] offset:3072
	s_waitcnt vmcnt(12)
	s_cmp_lt_u32 s10, 0x4000
	s_cbranch_scc0 .Llnl_pcA
	s_lshl_b32 s26, s10, 12
	s_add_u32 s26, s30, s26
	s_addc_u32 s27, s31, 0
	s_branch .Llnl_pjA
.Llnl_pcA:
	s_sub_u32 s26, s10, 0x4000
	s_lshl_b32 s26, s26, 12
	s_add_u32 s26, s88, s26
	s_addc_u32 s27, s89, 0
	s_add_u32 s26, s26, 0x28000
	s_addc_u32 s27, s27, 0
.Llnl_pjA:
	v_add_f32_e32 v6, v52, v53
	v_add_f32_e32 v6, v6, v54
	v_add_f32_e32 v6, v6, v55
	v_add_f32_e32 v6, v6, v56
	v_add_f32_e32 v6, v6, v57
	v_add_f32_e32 v6, v6, v58
	v_add_f32_e32 v6, v6, v59
	v_add_f32_e32 v6, v6, v60
	v_add_f32_e32 v6, v6, v61
	v_add_f32_e32 v6, v6, v62
	v_add_f32_e32 v6, v6, v63
	v_add_f32_e32 v6, v6, v64
	v_add_f32_e32 v6, v6, v65
	v_add_f32_e32 v6, v6, v66
	v_add_f32_e32 v6, v6, v67
	s_nop 1
	v_add_f32_dpp v6, v6, v6 row_ror:8 row_mask:0xf bank_mask:0xf bound_ctrl:1
	s_nop 1
	v_add_f32_dpp v6, v6, v6 row_ror:4 row_mask:0xf bank_mask:0xf bound_ctrl:1
	s_nop 1
	v_add_f32_dpp v6, v6, v6 row_ror:2 row_mask:0xf bank_mask:0xf bound_ctrl:1
	s_nop 1
	v_add_f32_dpp v6, v6, v6 row_ror:1 row_mask:0xf bank_mask:0xf bound_ctrl:1
	ds_bpermute_b32 v8, v5, v6
	s_waitcnt lgkmcnt(0)
;   DI float* xrow(int row) const { return row < MLAT ? p.out + (size_t)row * D : XC() + (size_t)(row - MLAT) * D; }
; DI void ln_row(const Ctx& c, int row, int l_post, int l_next, int lane) {
;     ...
;     if (do_post) {
;       float s = 0.f;
; #pragma unroll
;       for (int i = 0; i < 16; ++i) s += v[i];
;       const float mean = wave_sum(s) * (1.f / D);
;       float q = 0.f;
; #pragma unroll
;       for (int i = 0; i < 16; ++i) { v[i] -= mean; q += v[i] * v[i]; }
;       const float rstd = rsqrtf(wave_sum(q) * (1.f / D) + LN_EPS);
;       float* dst = c.xrow(row);
; #pragma unroll
;       for (int i = 0; i < 4; ++i) {
;         const int col = i * 256 + lane * 4;
;         const float4 g = *(const float4*)(p.post_g + l_post * D + col), b = *(const float4*)(p.post_b + l_post * D + col);
;         v[i * 4] = v[i * 4] * rstd * g.x + b.x; v[i * 4 + 1] = v[i * 4 + 1] * rstd * g.y + b.y;
;         v[i * 4 + 2] = v[i * 4 + 2] * rstd * g.z + b.z; v[i * 4 + 3] = v[i * 4 + 3] * rstd * g.w + b.w;
;         *(float4*)(dst + col) = make_float4(v[i * 4], v[i * 4 + 1], v[i * 4 + 2], v[i * 4 + 3]);
;       }
	v_add_f32_e32 v6, v6, v8
	v_mov_b32_e32 v8, v6
	s_nop 1
	v_permlane32_swap_b32_e32 v6, v8
	v_add_f32_e32 v6, v6, v8
	v_mul_f32_e32 v6, 0x3a800000, v6
	v_sub_f32_e32 v52, v52, v6
	v_sub_f32_e32 v53, v53, v6
	v_sub_f32_e32 v54, v54, v6
	v_sub_f32_e32 v55, v55, v6
	v_sub_f32_e32 v56, v56, v6
	v_sub_f32_e32 v57, v57, v6
	v_sub_f32_e32 v58, v58, v6
	v_sub_f32_e32 v59, v59, v6
	v_sub_f32_e32 v60, v60, v6
	v_sub_f32_e32 v61, v61, v6
	v_sub_f32_e32 v62, v62, v6
	v_sub_f32_e32 v63, v63, v6
	v_sub_f32_e32 v64, v64, v6
	v_sub_f32_e32 v65, v65, v6
	v_sub_f32_e32 v66, v66, v6
	v_sub_f32_e32 v67, v67, v6
	v_mul_f32_e32 v7, v52, v52
	v_fmac_f32_e32 v7, v53, v53
	v_fmac_f32_e32 v7, v54, v54
	v_fmac_f32_e32 v7, v55, v55
	v_fmac_f32_e32 v7, v56, v56
	v_fmac_f32_e32 v7, v57, v57
	v_fmac_f32_e32 v7, v58, v58
	v_fmac_f32_e32 v7, v59, v59
	v_fmac_f32_e32 v7, v60, v60
	v_fmac_f32_e32 v7, v61, v61
	v_fmac_f32_e32 v7, v62, v62
	v_fmac_f32_e32 v7, v63, v63
	v_fmac_f32_e32 v7, v64, v64
	v_fmac_f32_e32 v7, v65, v65
	v_fmac_f32_e32 v7, v66, v66
	v_fmac_f32_e32 v7, v67, v67
	s_nop 1
	v_add_f32_dpp v7, v7, v7 row_ror:8 row_mask:0xf bank_mask:0xf bound_ctrl:1
	s_nop 1
	v_add_f32_dpp v7, v7, v7 row_ror:4 row_mask:0xf bank_mask:0xf bound_ctrl:1
	s_nop 1
	v_add_f32_dpp v7, v7, v7 row_ror:2 row_mask:0xf bank_mask:0xf bound_ctrl:1
	s_nop 1
	v_add_f32_dpp v7, v7, v7 row_ror:1 row_mask:0xf bank_mask:0xf bound_ctrl:1
	ds_bpermute_b32 v8, v5, v7
	s_waitcnt lgkmcnt(0)
	v_add_f32_e32 v7, v7, v8
	v_mov_b32_e32 v8, v7
	s_nop 1
	v_permlane32_swap_b32_e32 v7, v8
	v_add_f32_e32 v7, v7, v8
	v_mov_b32_e32 v8, 0x358637bd
	v_fmac_f32_e32 v8, 0x3a800000, v7
	v_rsq_f32_e32 v7, v8
	s_nop 0
	v_mul_f32_e32 v52, v52, v7
	v_mul_f32_e32 v53, v53, v7
	v_mul_f32_e32 v54, v54, v7
	v_mul_f32_e32 v55, v55, v7
	v_mul_f32_e32 v56, v56, v7
	v_mul_f32_e32 v57, v57, v7
	v_mul_f32_e32 v58, v58, v7
	v_mul_f32_e32 v59, v59, v7
	v_mul_f32_e32 v60, v60, v7
	v_mul_f32_e32 v61, v61, v7
	v_mul_f32_e32 v62, v62, v7
	v_mul_f32_e32 v63, v63, v7
	v_mul_f32_e32 v64, v64, v7
	v_mul_f32_e32 v65, v65, v7
	v_mul_f32_e32 v66, v66, v7
	v_mul_f32_e32 v67, v67, v7
	v_fma_f32 v52, v52, v20, v36
	v_fma_f32 v53, v53, v21, v37
	v_fma_f32 v54, v54, v22, v38
	v_fma_f32 v55, v55, v23, v39
	v_fma_f32 v56, v56, v24, v40
	v_fma_f32 v57, v57, v25, v41
	v_fma_f32 v58, v58, v26, v42
	v_fma_f32 v59, v59, v27, v43
	v_fma_f32 v60, v60, v28, v44
	v_fma_f32 v61, v61, v29, v45
	v_fma_f32 v62, v62, v30, v46
	v_fma_f32 v63, v63, v31, v47
	v_fma_f32 v64, v64, v32, v48
	v_fma_f32 v65, v65, v33, v49
	v_fma_f32 v66, v66, v34, v50
	v_fma_f32 v67, v67, v35, v51
	global_store_dwordx4 v2, v[52:55], s[26:27] offset:0
	global_store_dwordx4 v2, v[56:59], s[26:27] offset:1024
	global_store_dwordx4 v2, v[60:63], s[26:27] offset:2048
	global_store_dwordx4 v2, v[64:67], s[26:27] offset:3072
	s_cmp_lt_u32 s86, 3
	s_cbranch_scc0 .Llnl_nohA
; DI bf16 f2bf(float f) { unsigned u = __float_as_uint(f); u += 0x7fffu + ((u >> 16) & 1u); return (bf16)(u >> 16); }
;   DI float* MOD() const { return (float*)(p.ws + WS_MOD); }
;   DI bf16* HY() const { return (bf16*)(p.ws + WS_HY); }
; DI void ln_row(const Ctx& c, int row, int l_post, int l_next, int lane) {
;     ...
;     if (do_h) {
;       float s = 0.f;
; #pragma unroll
;       for (int i = 0; i < 16; ++i) s += v[i];
;       const float mean = wave_sum(s) * (1.f / D);
;       float q = 0.f;
; #pragma unroll
;       for (int i = 0; i < 16; ++i) { v[i] -= mean; q += v[i] * v[i]; }
;       const float rstd = rsqrtf(wave_sum(q) * (1.f / D) + LN_EPS);
;       const float* md = c.MOD() + (l_next * 3 + mod_row(row)) * 3072;
;       bf16* dst = c.HY() + (size_t)row * D;
; #pragma unroll
;       for (int i = 0; i < 4; ++i) {
;         const int col = i * 256 + lane * 4;
;         const float4 sh = *(const float4*)(md + col), sc = *(const float4*)(md + 1024 + col);
;         const float h0 = v[i * 4] * rstd * (1.f + sc.x) + sh.x, h1 = v[i * 4 + 1] * rstd * (1.f + sc.y) + sh.y;
;         const float h2 = v[i * 4 + 2] * rstd * (1.f + sc.z) + sh.z, h3 = v[i * 4 + 3] * rstd * (1.f + sc.w) + sh.w;
;         uint2 pk; pk.x = (unsigned)f2bf(h0) | ((unsigned)f2bf(h1) << 16); pk.y = (unsigned)f2bf(h2) | ((unsigned)f2bf(h3) << 16);
;         *(uint2*)(dst + col) = pk;
;       }
	s_lshl_b32 s26, s10, 11
	s_add_u32 s26, s88, s26
	s_addc_u32 s27, s89, 0
	s_add_u32 s26, s26, 0x1128000
	s_addc_u32 s27, s27, 0
	v_add_f32_e32 v6, v52, v53
	v_add_f32_e32 v6, v6, v54
	v_add_f32_e32 v6, v6, v55
	v_add_f32_e32 v6, v6, v56
	v_add_f32_e32 v6, v6, v57
	v_add_f32_e32 v6, v6, v58
	v_add_f32_e32 v6, v6, v59
	v_add_f32_e32 v6, v6, v60
	v_add_f32_e32 v6, v6, v61
	v_add_f32_e32 v6, v6, v62
	v_add_f32_e32 v6, v6, v63
	v_add_f32_e32 v6, v6, v64
	v_add_f32_e32 v6, v6, v65
	v_add_f32_e32 v6, v6, v66
	v_add_f32_e32 v6, v6, v67
	s_nop 1
	v_add_f32_dpp v6, v6, v6 row_ror:8 row_mask:0xf bank_mask:0xf bound_ctrl:1
	s_nop 1
	v_add_f32_dpp v6, v6, v6 row_ror:4 row_mask:0xf bank_mask:0xf bound_ctrl:1
	s_nop 1
	v_add_f32_dpp v6, v6, v6 row_ror:2 row_mask:0xf bank_mask:0xf bound_ctrl:1
	s_nop 1
	v_add_f32_dpp v6, v6, v6 row_ror:1 row_mask:0xf bank_mask:0xf bound_ctrl:1
	ds_bpermute_b32 v8, v5, v6
	s_waitcnt lgkmcnt(0)
	v_add_f32_e32 v6, v6, v8
	v_mov_b32_e32 v8, v6
	s_nop 1
	v_permlane32_swap_b32_e32 v6, v8
	v_add_f32_e32 v6, v6, v8
	v_mul_f32_e32 v6, 0x3a800000, v6
	v_sub_f32_e32 v52, v52, v6
	v_sub_f32_e32 v53, v53, v6
	v_sub_f32_e32 v54, v54, v6
	v_sub_f32_e32 v55, v55, v6
	v_sub_f32_e32 v56, v56, v6
	v_sub_f32_e32 v57, v57, v6
	v_sub_f32_e32 v58, v58, v6
	v_sub_f32_e32 v59, v59, v6
	v_sub_f32_e32 v60, v60, v6
	v_sub_f32_e32 v61, v61, v6
	v_sub_f32_e32 v62, v62, v6
	v_sub_f32_e32 v63, v63, v6
	v_sub_f32_e32 v64, v64, v6
	v_sub_f32_e32 v65, v65, v6
	v_sub_f32_e32 v66, v66, v6
	v_sub_f32_e32 v67, v67, v6
	v_mul_f32_e32 v7, v52, v52
	v_fmac_f32_e32 v7, v53, v53
	v_fmac_f32_e32 v7, v54, v54
	v_fmac_f32_e32 v7, v55, v55
	v_fmac_f32_e32 v7, v56, v56
	v_fmac_f32_e32 v7, v57, v57
	v_fmac_f32_e32 v7, v58, v58
	v_fmac_f32_e32 v7, v59, v59
	v_fmac_f32_e32 v7, v60, v60
	v_fmac_f32_e32 v7, v61, v61
	v_fmac_f32_e32 v7, v62, v62
	v_fmac_f32_e32 v7, v63, v63
	v_fmac_f32_e32 v7, v64, v64
	v_fmac_f32_e32 v7, v65, v65
	v_fmac_f32_e32 v7, v66, v66
	v_fmac_f32_e32 v7, v67, v67
	s_nop 1
	v_add_f32_dpp v7, v7, v7 row_ror:8 row_mask:0xf bank_mask:0xf bound_ctrl:1
	s_nop 1
	v_add_f32_dpp v7, v7, v7 row_ror:4 row_mask:0xf bank_mask:0xf bound_ctrl:1
	s_nop 1
	v_add_f32_dpp v7, v7, v7 row_ror:2 row_mask:0xf bank_mask:0xf bound_ctrl:1
	s_nop 1
	v_add_f32_dpp v7, v7, v7 row_ror:1 row_mask:0xf bank_mask:0xf bound_ctrl:1
	ds_bpermute_b32 v8, v5, v7
	s_waitcnt lgkmcnt(0)
	v_add_f32_e32 v7, v7, v8
	v_mov_b32_e32 v8, v7
	s_nop 1
	v_permlane32_swap_b32_e32 v7, v8
	v_add_f32_e32 v7, v7, v8
	v_mov_b32_e32 v8, 0x358637bd
	v_fmac_f32_e32 v8, 0x3a800000, v7
	v_rsq_f32_e32 v7, v8
	s_nop 0
	v_mul_f32_e32 v52, v52, v7
	v_mul_f32_e32 v53, v53, v7
	v_mul_f32_e32 v54, v54, v7
	v_mul_f32_e32 v55, v55, v7
	v_mul_f32_e32 v56, v56, v7
	v_mul_f32_e32 v57, v57, v7
	v_mul_f32_e32 v58, v58, v7
	v_mul_f32_e32 v59, v59, v7
	v_mul_f32_e32 v60, v60, v7
	v_mul_f32_e32 v61, v61, v7
	v_mul_f32_e32 v62, v62, v7
	v_mul_f32_e32 v63, v63, v7
	v_mul_f32_e32 v64, v64, v7
	v_mul_f32_e32 v65, v65, v7
	v_mul_f32_e32 v66, v66, v7
	v_mul_f32_e32 v67, v67, v7
	v_add_f32_e32 v100, 1.0, v100
	v_add_f32_e32 v101, 1.0, v101
	v_add_f32_e32 v102, 1.0, v102
	v_add_f32_e32 v103, 1.0, v103
	v_add_f32_e32 v104, 1.0, v104
	v_add_f32_e32 v105, 1.0, v105
	v_add_f32_e32 v106, 1.0, v106
	v_add_f32_e32 v107, 1.0, v107
	v_add_f32_e32 v108, 1.0, v108
	v_add_f32_e32 v109, 1.0, v109
	v_add_f32_e32 v110, 1.0, v110
	v_add_f32_e32 v111, 1.0, v111
	v_add_f32_e32 v112, 1.0, v112
	v_add_f32_e32 v113, 1.0, v113
	v_add_f32_e32 v114, 1.0, v114
	v_add_f32_e32 v115, 1.0, v115
	v_fma_f32 v52, v52, v100, v84
	v_fma_f32 v53, v53, v101, v85
	v_fma_f32 v54, v54, v102, v86
	v_fma_f32 v55, v55, v103, v87
	v_fma_f32 v56, v56, v104, v88
	v_fma_f32 v57, v57, v105, v89
	v_fma_f32 v58, v58, v106, v90
	v_fma_f32 v59, v59, v107, v91
	v_fma_f32 v60, v60, v108, v92
	v_fma_f32 v61, v61, v109, v93
	v_fma_f32 v62, v62, v110, v94
	v_fma_f32 v63, v63, v111, v95
	v_fma_f32 v64, v64, v112, v96
	v_fma_f32 v65, v65, v113, v97
	v_fma_f32 v66, v66, v114, v98
	v_fma_f32 v67, v67, v115, v99
	v_cvt_pk_bf16_f32 v52, v52, v53
	v_cvt_pk_bf16_f32 v53, v54, v55
	v_cvt_pk_bf16_f32 v54, v56, v57
	v_cvt_pk_bf16_f32 v55, v58, v59
	v_cvt_pk_bf16_f32 v56, v60, v61
	v_cvt_pk_bf16_f32 v57, v62, v63
	v_cvt_pk_bf16_f32 v58, v64, v65
	v_cvt_pk_bf16_f32 v59, v66, v67
	global_store_dwordx2 v14, v[52:53], s[26:27] offset:0
	global_store_dwordx2 v14, v[54:55], s[26:27] offset:512
	global_store_dwordx2 v14, v[56:57], s[26:27] offset:1024
	global_store_dwordx2 v14, v[58:59], s[26:27] offset:1536
.Llnl_nohA:
	s_mov_b32 s10, s12
	s_branch .Llnl_nextB
.Llnl_lastA:
	s_waitcnt vmcnt(0)
	s_cmp_lt_u32 s10, 0x4000
	s_cbranch_scc0 .Llnl_pcAl
	s_lshl_b32 s26, s10, 12
	s_add_u32 s26, s30, s26
	s_addc_u32 s27, s31, 0
	s_branch .Llnl_pjAl

;   DI float* MOD() const { return (float*)(p.ws + WS_MOD); }
;   DI bf16* HY() const { return (bf16*)(p.ws + WS_HY); }
;   DI float* xrow(int row) const { return row < MLAT ? p.out + (size_t)row * D : XC() + (size_t)(row - MLAT) * D; }
; DI void ln_row(const Ctx& c, int row, int l_post, int l_next, int lane) {
;     ...
;     const float* src = (l_post < 0) ? c.xin(row) : c.xrow(row);
;     ...
;       const float* md = c.MOD() + (l_next * 3 + mod_row(row)) * 3072;
;       bf16* dst = c.HY() + (size_t)row * D;
; DI void phase_ln(const Ctx& c, int l_post, int l_next) {
;     ...
;   for (int row = wv; row < MT; row += 2 * nw) { ln_row(c, row, l_post, l_next, lane); if (row + nw < MT) ln_row(c, row + nw, l_post, l_next, lane); }
.Llnl_j2:
	global_load_dwordx4 v[52:55], v2, s[2:3] offset:0
	global_load_dwordx4 v[56:59], v2, s[2:3] offset:1024
	global_load_dwordx4 v[60:63], v2, s[2:3] offset:2048
	global_load_dwordx4 v[64:67], v2, s[2:3] offset:3072
	s_add_u32 s14, s14, s20
	s_mul_i32 s14, s14, 0x3000
	s_add_u32 s24, s88, s14
	s_addc_u32 s25, s89, 0
	s_add_u32 s24, s24, 0x4000
	s_addc_u32 s25, s25, 0
	global_load_dwordx4 v[84:87], v2, s[24:25] offset:0
	global_load_dwordx4 v[88:91], v2, s[24:25] offset:1024
	global_load_dwordx4 v[92:95], v2, s[24:25] offset:2048
	global_load_dwordx4 v[96:99], v2, s[24:25] offset:3072
	s_add_u32 s24, s24, 0x1000
	s_addc_u32 s25, s25, 0
	global_load_dwordx4 v[100:103], v2, s[24:25] offset:0
	global_load_dwordx4 v[104:107], v2, s[24:25] offset:1024
	global_load_dwordx4 v[108:111], v2, s[24:25] offset:2048
	global_load_dwordx4 v[112:115], v2, s[24:25] offset:3072
	s_waitcnt vmcnt(12)
	s_cmp_lt_u32 s10, 0x4000
	s_cbranch_scc0 .Llnl_pcB
	s_lshl_b32 s26, s10, 12
	s_add_u32 s26, s30, s26
	s_addc_u32 s27, s31, 0
	s_branch .Llnl_pjB

;   DI float* xrow(int row) const { return row < MLAT ? p.out + (size_t)row * D : XC() + (size_t)(row - MLAT) * D; }
; DI void ln_row(const Ctx& c, int row, int l_post, int l_next, int lane) {
;     ...
;     if (do_post) {
;       float s = 0.f;
; #pragma unroll
;       for (int i = 0; i < 16; ++i) s += v[i];
;       const float mean = wave_sum(s) * (1.f / D);
;       float q = 0.f;
; #pragma unroll
;       for (int i = 0; i < 16; ++i) { v[i] -= mean; q += v[i] * v[i]; }
;       const float rstd = rsqrtf(wave_sum(q) * (1.f / D) + LN_EPS);
;       float* dst = c.xrow(row);
; #pragma unroll
;       for (int i = 0; i < 4; ++i) {
;         const int col = i * 256 + lane * 4;
;         const float4 g = *(const float4*)(p.post_g + l_post * D + col), b = *(const float4*)(p.post_b + l_post * D + col);
;         v[i * 4] = v[i * 4] * rstd * g.x + b.x; v[i * 4 + 1] = v[i * 4 + 1] * rstd * g.y + b.y;
;         v[i * 4 + 2] = v[i * 4 + 2] * rstd * g.z + b.z; v[i * 4 + 3] = v[i * 4 + 3] * rstd * g.w + b.w;
;         *(float4*)(dst + col) = make_float4(v[i * 4], v[i * 4 + 1], v[i * 4 + 2], v[i * 4 + 3]);
;       }
.Llnl_pjB:
	v_add_f32_e32 v6, v68, v69
	v_add_f32_e32 v6, v6, v70
	v_add_f32_e32 v6, v6, v71
	v_add_f32_e32 v6, v6, v72
	v_add_f32_e32 v6, v6, v73
	v_add_f32_e32 v6, v6, v74
	v_add_f32_e32 v6, v6, v75
	v_add_f32_e32 v6, v6, v76
	v_add_f32_e32 v6, v6, v77
	v_add_f32_e32 v6, v6, v78
	v_add_f32_e32 v6, v6, v79
	v_add_f32_e32 v6, v6, v80
	v_add_f32_e32 v6, v6, v81
	v_add_f32_e32 v6, v6, v82
	v_add_f32_e32 v6, v6, v83
	s_nop 1
	v_add_f32_dpp v6, v6, v6 row_ror:8 row_mask:0xf bank_mask:0xf bound_ctrl:1
	s_nop 1
	v_add_f32_dpp v6, v6, v6 row_ror:4 row_mask:0xf bank_mask:0xf bound_ctrl:1
	s_nop 1
	v_add_f32_dpp v6, v6, v6 row_ror:2 row_mask:0xf bank_mask:0xf bound_ctrl:1
	s_nop 1
	v_add_f32_dpp v6, v6, v6 row_ror:1 row_mask:0xf bank_mask:0xf bound_ctrl:1
	ds_bpermute_b32 v8, v5, v6
	s_waitcnt lgkmcnt(0)
	v_add_f32_e32 v6, v6, v8
	v_mov_b32_e32 v8, v6
	s_nop 1
	v_permlane32_swap_b32_e32 v6, v8
	v_add_f32_e32 v6, v6, v8
	v_mul_f32_e32 v6, 0x3a800000, v6
	v_sub_f32_e32 v68, v68, v6
	v_sub_f32_e32 v69, v69, v6
	v_sub_f32_e32 v70, v70, v6
	v_sub_f32_e32 v71, v71, v6
	v_sub_f32_e32 v72, v72, v6
	v_sub_f32_e32 v73, v73, v6
	v_sub_f32_e32 v74, v74, v6
	v_sub_f32_e32 v75, v75, v6
	v_sub_f32_e32 v76, v76, v6
	v_sub_f32_e32 v77, v77, v6
	v_sub_f32_e32 v78, v78, v6
	v_sub_f32_e32 v79, v79, v6
	v_sub_f32_e32 v80, v80, v6
	v_sub_f32_e32 v81, v81, v6
	v_sub_f32_e32 v82, v82, v6
	v_sub_f32_e32 v83, v83, v6
	v_mul_f32_e32 v7, v68, v68
	v_fmac_f32_e32 v7, v69, v69
	v_fmac_f32_e32 v7, v70, v70
	v_fmac_f32_e32 v7, v71, v71
	v_fmac_f32_e32 v7, v72, v72
	v_fmac_f32_e32 v7, v73, v73
	v_fmac_f32_e32 v7, v74, v74
	v_fmac_f32_e32 v7, v75, v75
	v_fmac_f32_e32 v7, v76, v76
	v_fmac_f32_e32 v7, v77, v77
	v_fmac_f32_e32 v7, v78, v78
	v_fmac_f32_e32 v7, v79, v79
	v_fmac_f32_e32 v7, v80, v80
	v_fmac_f32_e32 v7, v81, v81
	v_fmac_f32_e32 v7, v82, v82
	v_fmac_f32_e32 v7, v83, v83
	s_nop 1
	v_add_f32_dpp v7, v7, v7 row_ror:8 row_mask:0xf bank_mask:0xf bound_ctrl:1
	s_nop 1
	v_add_f32_dpp v7, v7, v7 row_ror:4 row_mask:0xf bank_mask:0xf bound_ctrl:1
	s_nop 1
	v_add_f32_dpp v7, v7, v7 row_ror:2 row_mask:0xf bank_mask:0xf bound_ctrl:1
	s_nop 1
	v_add_f32_dpp v7, v7, v7 row_ror:1 row_mask:0xf bank_mask:0xf bound_ctrl:1
	ds_bpermute_b32 v8, v5, v7
	s_waitcnt lgkmcnt(0)
	v_add_f32_e32 v7, v7, v8
	v_mov_b32_e32 v8, v7
	s_nop 1
	v_permlane32_swap_b32_e32 v7, v8
	v_add_f32_e32 v7, v7, v8
	v_mov_b32_e32 v8, 0x358637bd
	v_fmac_f32_e32 v8, 0x3a800000, v7
	v_rsq_f32_e32 v7, v8
	s_nop 0
	v_mul_f32_e32 v68, v68, v7
	v_mul_f32_e32 v69, v69, v7
	v_mul_f32_e32 v70, v70, v7
	v_mul_f32_e32 v71, v71, v7
	v_mul_f32_e32 v72, v72, v7
	v_mul_f32_e32 v73, v73, v7
	v_mul_f32_e32 v74, v74, v7
	v_mul_f32_e32 v75, v75, v7
	v_mul_f32_e32 v76, v76, v7
	v_mul_f32_e32 v77, v77, v7
	v_mul_f32_e32 v78, v78, v7
	v_mul_f32_e32 v79, v79, v7
	v_mul_f32_e32 v80, v80, v7
	v_mul_f32_e32 v81, v81, v7
	v_mul_f32_e32 v82, v82, v7
	v_mul_f32_e32 v83, v83, v7
	v_fma_f32 v68, v68, v20, v36
	v_fma_f32 v69, v69, v21, v37
	v_fma_f32 v70, v70, v22, v38
	v_fma_f32 v71, v71, v23, v39
	v_fma_f32 v72, v72, v24, v40
	v_fma_f32 v73, v73, v25, v41
	v_fma_f32 v74, v74, v26, v42
	v_fma_f32 v75, v75, v27, v43
	v_fma_f32 v76, v76, v28, v44
	v_fma_f32 v77, v77, v29, v45
	v_fma_f32 v78, v78, v30, v46
	v_fma_f32 v79, v79, v31, v47
	v_fma_f32 v80, v80, v32, v48
	v_fma_f32 v81, v81, v33, v49
	v_fma_f32 v82, v82, v34, v50
	v_fma_f32 v83, v83, v35, v51
	global_store_dwordx4 v2, v[68:71], s[26:27] offset:0
	global_store_dwordx4 v2, v[72:75], s[26:27] offset:1024
	global_store_dwordx4 v2, v[76:79], s[26:27] offset:2048
	global_store_dwordx4 v2, v[80:83], s[26:27] offset:3072
	s_cmp_lt_u32 s86, 3
	s_cbranch_scc0 .Llnl_nohB
; DI bf16 f2bf(float f) { unsigned u = __float_as_uint(f); u += 0x7fffu + ((u >> 16) & 1u); return (bf16)(u >> 16); }
;   DI float* MOD() const { return (float*)(p.ws + WS_MOD); }
;   DI bf16* HY() const { return (bf16*)(p.ws + WS_HY); }
; DI void ln_row(const Ctx& c, int row, int l_post, int l_next, int lane) {
;     ...
;     if (do_h) {
;       float s = 0.f;
; #pragma unroll
;       for (int i = 0; i < 16; ++i) s += v[i];
;       const float mean = wave_sum(s) * (1.f / D);
;       float q = 0.f;
; #pragma unroll
;       for (int i = 0; i < 16; ++i) { v[i] -= mean; q += v[i] * v[i]; }
;       const float rstd = rsqrtf(wave_sum(q) * (1.f / D) + LN_EPS);
;       const float* md = c.MOD() + (l_next * 3 + mod_row(row)) * 3072;
;       bf16* dst = c.HY() + (size_t)row * D;
; #pragma unroll
;       for (int i = 0; i < 4; ++i) {
;         const int col = i * 256 + lane * 4;
;         const float4 sh = *(const float4*)(md + col), sc = *(const float4*)(md + 1024 + col);
;         const float h0 = v[i * 4] * rstd * (1.f + sc.x) + sh.x, h1 = v[i * 4 + 1] * rstd * (1.f + sc.y) + sh.y;
;         const float h2 = v[i * 4 + 2] * rstd * (1.f + sc.z) + sh.z, h3 = v[i * 4 + 3] * rstd * (1.f + sc.w) + sh.w;
;         uint2 pk; pk.x = (unsigned)f2bf(h0) | ((unsigned)f2bf(h1) << 16); pk.y = (unsigned)f2bf(h2) | ((unsigned)f2bf(h3) << 16);
;         *(uint2*)(dst + col) = pk;
;       }
	s_lshl_b32 s26, s10, 11
	s_add_u32 s26, s88, s26
	s_addc_u32 s27, s89, 0
	s_add_u32 s26, s26, 0x1128000
	s_addc_u32 s27, s27, 0
	v_add_f32_e32 v6, v68, v69
	v_add_f32_e32 v6, v6, v70
	v_add_f32_e32 v6, v6, v71
	v_add_f32_e32 v6, v6, v72
	v_add_f32_e32 v6, v6, v73
	v_add_f32_e32 v6, v6, v74
	v_add_f32_e32 v6, v6, v75
	v_add_f32_e32 v6, v6, v76
	v_add_f32_e32 v6, v6, v77
	v_add_f32_e32 v6, v6, v78
	v_add_f32_e32 v6, v6, v79
	v_add_f32_e32 v6, v6, v80
	v_add_f32_e32 v6, v6, v81
	v_add_f32_e32 v6, v6, v82
	v_add_f32_e32 v6, v6, v83
	s_nop 1
	v_add_f32_dpp v6, v6, v6 row_ror:8 row_mask:0xf bank_mask:0xf bound_ctrl:1
	s_nop 1
	v_add_f32_dpp v6, v6, v6 row_ror:4 row_mask:0xf bank_mask:0xf bound_ctrl:1
	s_nop 1
	v_add_f32_dpp v6, v6, v6 row_ror:2 row_mask:0xf bank_mask:0xf bound_ctrl:1
	s_nop 1
	v_add_f32_dpp v6, v6, v6 row_ror:1 row_mask:0xf bank_mask:0xf bound_ctrl:1
	ds_bpermute_b32 v8, v5, v6
	s_waitcnt lgkmcnt(0)
	v_add_f32_e32 v6, v6, v8
	v_mov_b32_e32 v8, v6
	s_nop 1
	v_permlane32_swap_b32_e32 v6, v8
	v_add_f32_e32 v6, v6, v8
	v_mul_f32_e32 v6, 0x3a800000, v6
	v_sub_f32_e32 v68, v68, v6
	v_sub_f32_e32 v69, v69, v6
	v_sub_f32_e32 v70, v70, v6
	v_sub_f32_e32 v71, v71, v6
	v_sub_f32_e32 v72, v72, v6
	v_sub_f32_e32 v73, v73, v6
	v_sub_f32_e32 v74, v74, v6
	v_sub_f32_e32 v75, v75, v6
	v_sub_f32_e32 v76, v76, v6
	v_sub_f32_e32 v77, v77, v6
	v_sub_f32_e32 v78, v78, v6
	v_sub_f32_e32 v79, v79, v6
	v_sub_f32_e32 v80, v80, v6
	v_sub_f32_e32 v81, v81, v6
	v_sub_f32_e32 v82, v82, v6
	v_sub_f32_e32 v83, v83, v6
	v_mul_f32_e32 v7, v68, v68
	v_fmac_f32_e32 v7, v69, v69
	v_fmac_f32_e32 v7, v70, v70
	v_fmac_f32_e32 v7, v71, v71
	v_fmac_f32_e32 v7, v72, v72
	v_fmac_f32_e32 v7, v73, v73
	v_fmac_f32_e32 v7, v74, v74
	v_fmac_f32_e32 v7, v75, v75
	v_fmac_f32_e32 v7, v76, v76
	v_fmac_f32_e32 v7, v77, v77
	v_fmac_f32_e32 v7, v78, v78
	v_fmac_f32_e32 v7, v79, v79
	v_fmac_f32_e32 v7, v80, v80
	v_fmac_f32_e32 v7, v81, v81
	v_fmac_f32_e32 v7, v82, v82
	v_fmac_f32_e32 v7, v83, v83
	s_nop 1
	v_add_f32_dpp v7, v7, v7 row_ror:8 row_mask:0xf bank_mask:0xf bound_ctrl:1
	s_nop 1
	v_add_f32_dpp v7, v7, v7 row_ror:4 row_mask:0xf bank_mask:0xf bound_ctrl:1
	s_nop 1
	v_add_f32_dpp v7, v7, v7 row_ror:2 row_mask:0xf bank_mask:0xf bound_ctrl:1
	s_nop 1
	v_add_f32_dpp v7, v7, v7 row_ror:1 row_mask:0xf bank_mask:0xf bound_ctrl:1
	ds_bpermute_b32 v8, v5, v7
	s_waitcnt lgkmcnt(0)
	v_add_f32_e32 v7, v7, v8
	v_mov_b32_e32 v8, v7
	s_nop 1
	v_permlane32_swap_b32_e32 v7, v8
	v_add_f32_e32 v7, v7, v8
	v_mov_b32_e32 v8, 0x358637bd
	v_fmac_f32_e32 v8, 0x3a800000, v7
	v_rsq_f32_e32 v7, v8
	s_nop 0
	v_mul_f32_e32 v68, v68, v7
	v_mul_f32_e32 v69, v69, v7
	v_mul_f32_e32 v70, v70, v7
	v_mul_f32_e32 v71, v71, v7
	v_mul_f32_e32 v72, v72, v7
	v_mul_f32_e32 v73, v73, v7
	v_mul_f32_e32 v74, v74, v7
	v_mul_f32_e32 v75, v75, v7
	v_mul_f32_e32 v76, v76, v7
	v_mul_f32_e32 v77, v77, v7
	v_mul_f32_e32 v78, v78, v7
	v_mul_f32_e32 v79, v79, v7
	v_mul_f32_e32 v80, v80, v7
	v_mul_f32_e32 v81, v81, v7
	v_mul_f32_e32 v82, v82, v7
	v_mul_f32_e32 v83, v83, v7
	v_add_f32_e32 v132, 1.0, v132
	v_add_f32_e32 v133, 1.0, v133
	v_add_f32_e32 v134, 1.0, v134
	v_add_f32_e32 v135, 1.0, v135
	v_add_f32_e32 v136, 1.0, v136
	v_add_f32_e32 v137, 1.0, v137
	v_add_f32_e32 v138, 1.0, v138
	v_add_f32_e32 v139, 1.0, v139
	v_add_f32_e32 v140, 1.0, v140
	v_add_f32_e32 v141, 1.0, v141
	v_add_f32_e32 v142, 1.0, v142
	v_add_f32_e32 v143, 1.0, v143
	v_add_f32_e32 v144, 1.0, v144
	v_add_f32_e32 v145, 1.0, v145
	v_add_f32_e32 v146, 1.0, v146
	v_add_f32_e32 v147, 1.0, v147
	v_fma_f32 v68, v68, v132, v116
	v_fma_f32 v69, v69, v133, v117
	v_fma_f32 v70, v70, v134, v118
	v_fma_f32 v71, v71, v135, v119
	v_fma_f32 v72, v72, v136, v120
	v_fma_f32 v73, v73, v137, v121
	v_fma_f32 v74, v74, v138, v122
	v_fma_f32 v75, v75, v139, v123
	v_fma_f32 v76, v76, v140, v124
	v_fma_f32 v77, v77, v141, v125
	v_fma_f32 v78, v78, v142, v126
	v_fma_f32 v79, v79, v143, v127
	v_fma_f32 v80, v80, v144, v128
	v_fma_f32 v81, v81, v145, v129
	v_fma_f32 v82, v82, v146, v130
	v_fma_f32 v83, v83, v147, v131
	v_cvt_pk_bf16_f32 v68, v68, v69
	v_cvt_pk_bf16_f32 v69, v70, v71
	v_cvt_pk_bf16_f32 v70, v72, v73
	v_cvt_pk_bf16_f32 v71, v74, v75
	v_cvt_pk_bf16_f32 v72, v76, v77
	v_cvt_pk_bf16_f32 v73, v78, v79
	v_cvt_pk_bf16_f32 v74, v80, v81
	v_cvt_pk_bf16_f32 v75, v82, v83
	global_store_dwordx2 v14, v[68:69], s[26:27] offset:0
	global_store_dwordx2 v14, v[70:71], s[26:27] offset:512
	global_store_dwordx2 v14, v[72:73], s[26:27] offset:1024
	global_store_dwordx2 v14, v[74:75], s[26:27] offset:1536

; DI void phase_ln(const Ctx& c, int l_post, int l_next) {
;     ...
;   for (int row = wv; row < MT; row += 2 * nw) { ln_row(c, row, l_post, l_next, lane); if (row + nw < MT) ln_row(c, row + nw, l_post, l_next, lane); }
.Llnl_nohBl:
	s_branch .Llnl_exit
.Llnl_exit:
	s_branch .LBB0_1180
.LBB0_1180:
	s_or_b64 exec, exec, s[8:9]
	s_and_b64 vcc, exec, s[4:5]
	s_cbranch_vccz .LBB0_1181
	s_getpc_b64 s[98:99]
